# conv main path rewritten (16 rows in flight) + wave-to-token rotation spreading sequence-boundary tokens; acc zeroing with v_mov_b64
# speedup vs baseline: 1.0527x; 1.0151x over previous
; __device__ __forceinline__ u32x4 pack8(f32x4 a, f32x4 b) { u32x4 w; w.x = pk2(a[0], a[1]); w.y = pk2(a[2], a[3]); w.z = pk2(b[0], b[1]); w.w = pk2(b[2], b[3]); return w; }
; __device__ __forceinline__ f32x4 sigm4(f32x4 v) { return (f32x4){sigm(v[0]), sigm(v[1]), sigm(v[2]), sigm(v[3])}; }
; __device__ __forceinline__ void phase_conv(CParams& p, LAS unsigned char* lds) {
;     ...
;         *(u32x4*)(p.sconv + (size_t)mm * DCV + ch0) = pack8(c0 * sigm4(c0), c1 * sigm4(c1));
;     ...
;     for (int mp = gw; mp < MP / 2; mp += nw) {
;         const int m = mp * 2, t = m & 4095;
.LBB0_207:
	s_or_b64 exec, exec, s[10:11]
	v_ashrrev_i32_e32 v73, 31, v72
	s_cmpk_eq_i32 s64, 0x800
	s_cbranch_scc0 .Lconv_norot
	v_add_u32_e32 v28, 16, v74
	v_and_b32_e32 v28, 0x7ff, v28
	v_and_b32_e32 v29, 0xfffff800, v74
	v_add_u32_e32 v29, 0x800, v29
	v_or_b32_e32 v74, v28, v29
	s_branch .Lconv_rotdone
.Lconv_norot:
	v_add_u32_e32 v74, s64, v74
.Lconv_rotdone:
	s_movk_i32 s0, 0x3fff
	v_lshlrev_b64 v[28:29], 10, v[72:73]
	v_cmp_lt_i32_e32 vcc, s0, v74
	v_readlane_b32 s0, v245, 0
	v_lshl_add_u64 v[28:29], v[68:69], 0, v[28:29]
	s_or_b64 s[20:21], vcc, s[20:21]
	v_lshlrev_b32_e32 v76, 1, v74
	global_store_dwordx4 v[28:29], v[24:27], off
	s_andn2_b64 exec, exec, s[20:21]
	s_cbranch_execz .LBB0_216

; #define LAS __attribute__((address_space(3)))
; __device__ __forceinline__ void unpack8(u32x4 w, f32x4& a, f32x4& b) { a = (f32x4){bf_lo(w.x), bf_hi(w.x), bf_lo(w.y), bf_hi(w.y)}; b = (f32x4){bf_lo(w.z), bf_hi(w.z), bf_lo(w.w), bf_hi(w.w)}; }
; __device__ __forceinline__ void phase_conv(CParams& p, LAS unsigned char* lds) {
;     ...
;             u32x4 xr[32];
;             const bf16_t* up = p.u + (size_t)(m - 30) * DCV + ch0;
; #pragma unroll
;             for (int j = 0; j < 32; ++j) xr[j] = *(const u32x4*)(up + (size_t)j * DCV);
;             f32x4 a0 = bd0, a1 = bd1, b0 = bd0, b1 = bd1, x0, x1, y0, y1;
;             unpack8(xr[0], x0, x1);
; #pragma unroll
;             for (int j = 0; j < 31; ++j) {
;                 unpack8(xr[j + 1], y0, y1);
;                 const f32x4 w0 = *(const LAS f32x4*)(wl + j * 512 + ch0), w1 = *(const LAS f32x4*)(wl + j * 512 + ch0 + 4);
;                 a0 += x0 * w0; a1 += x1 * w1; b0 += y0 * w0; b1 += y1 * w1;
;                 x0 = y0; x1 = y1;
;             }
.LBB0_214:
	s_andn2_saveexec_b64 s[10:11], s[22:23]
	s_cbranch_execz .LBB0_207
	s_mov_b64 s[6:7], 0x1000
	v_subrev_u32_e32 v242, 30, v70
	v_ashrrev_i32_e32 v243, 31, v242
	v_lshlrev_b64 v[242:243], 10, v[242:243]
	v_lshl_add_u64 v[240:241], v[66:67], 0, v[242:243]
	global_load_dwordx4 v[28:31], v[240:241], off offset:0
	global_load_dwordx4 v[32:35], v[240:241], off offset:1024
	global_load_dwordx4 v[36:39], v[240:241], off offset:2048
	global_load_dwordx4 v[40:43], v[240:241], off offset:3072
	s_nop 0
	v_lshl_add_u64 v[240:241], v[240:241], 0, s[6:7]
	global_load_dwordx4 v[44:47], v[240:241], off offset:0
	global_load_dwordx4 v[48:51], v[240:241], off offset:1024
	global_load_dwordx4 v[52:55], v[240:241], off offset:2048
	global_load_dwordx4 v[56:59], v[240:241], off offset:3072
	s_nop 0
	v_lshl_add_u64 v[240:241], v[240:241], 0, s[6:7]
	global_load_dwordx4 v[60:63], v[240:241], off offset:0
	global_load_dwordx4 v[80:83], v[240:241], off offset:1024
	global_load_dwordx4 v[84:87], v[240:241], off offset:2048
	global_load_dwordx4 v[92:95], v[240:241], off offset:3072
	s_nop 0
	v_lshl_add_u64 v[240:241], v[240:241], 0, s[6:7]
	global_load_dwordx4 v[96:99], v[240:241], off offset:0
	global_load_dwordx4 v[100:103], v[240:241], off offset:1024
	global_load_dwordx4 v[104:107], v[240:241], off offset:2048
	global_load_dwordx4 v[108:111], v[240:241], off offset:3072
	s_nop 0
	v_lshl_add_u64 v[240:241], v[240:241], 0, s[6:7]
	s_waitcnt vmcnt(16)
	v_mov_b64_e32 v[112:113], v[8:9]
	v_mov_b64_e32 v[172:173], v[8:9]
	v_mov_b64_e32 v[114:115], v[10:11]
	v_mov_b64_e32 v[174:175], v[10:11]
	v_mov_b64_e32 v[116:117], v[0:1]
	v_mov_b64_e32 v[176:177], v[0:1]
	v_mov_b64_e32 v[90:91], v[2:3]
	v_mov_b64_e32 v[178:179], v[2:3]
	ds_read_b128 v[188:191], v75 offset:0
	ds_read_b128 v[220:223], v75 offset:16
	ds_read_b128 v[224:227], v75 offset:2048
	ds_read_b128 v[228:231], v75 offset:2064
	s_waitcnt vmcnt(15)
	v_lshlrev_b32_e32 v180, 16, v28
	v_and_b32_e32 v181, 0xffff0000, v28
	v_lshlrev_b32_e32 v182, 16, v29
	v_and_b32_e32 v183, 0xffff0000, v29
	v_lshlrev_b32_e32 v184, 16, v30
	v_and_b32_e32 v185, 0xffff0000, v30
	v_lshlrev_b32_e32 v186, 16, v31
	v_and_b32_e32 v187, 0xffff0000, v31
	global_load_dwordx4 v[28:31], v[240:241], off offset:0
	s_waitcnt lgkmcnt(3)
	v_pk_fma_f32 v[112:113], v[180:181], v[188:189], v[112:113]
	v_pk_fma_f32 v[114:115], v[182:183], v[190:191], v[114:115]
	s_waitcnt lgkmcnt(2)
	v_pk_fma_f32 v[116:117], v[184:185], v[220:221], v[116:117]
	v_pk_fma_f32 v[90:91], v[186:187], v[222:223], v[90:91]
	ds_read_b128 v[232:235], v75 offset:4096
	ds_read_b128 v[236:239], v75 offset:4112
	s_waitcnt vmcnt(15)
	v_lshlrev_b32_e32 v180, 16, v32
	v_and_b32_e32 v181, 0xffff0000, v32
	v_lshlrev_b32_e32 v182, 16, v33
	v_and_b32_e32 v183, 0xffff0000, v33
	v_lshlrev_b32_e32 v184, 16, v34
	v_and_b32_e32 v185, 0xffff0000, v34
	v_lshlrev_b32_e32 v186, 16, v35
	v_and_b32_e32 v187, 0xffff0000, v35
	global_load_dwordx4 v[32:35], v[240:241], off offset:1024
	s_waitcnt lgkmcnt(3)
	v_pk_fma_f32 v[112:113], v[180:181], v[224:225], v[112:113]
	v_pk_fma_f32 v[114:115], v[182:183], v[226:227], v[114:115]
	s_waitcnt lgkmcnt(2)
	v_pk_fma_f32 v[116:117], v[184:185], v[228:229], v[116:117]
	v_pk_fma_f32 v[90:91], v[186:187], v[230:231], v[90:91]
	v_pk_fma_f32 v[172:173], v[180:181], v[188:189], v[172:173]
	v_pk_fma_f32 v[174:175], v[182:183], v[190:191], v[174:175]
	v_pk_fma_f32 v[176:177], v[184:185], v[220:221], v[176:177]
	v_pk_fma_f32 v[178:179], v[186:187], v[222:223], v[178:179]
	ds_read_b128 v[188:191], v75 offset:6144
	ds_read_b128 v[220:223], v75 offset:6160
	s_waitcnt vmcnt(15)
	v_lshlrev_b32_e32 v180, 16, v36
	v_and_b32_e32 v181, 0xffff0000, v36
	v_lshlrev_b32_e32 v182, 16, v37
	v_and_b32_e32 v183, 0xffff0000, v37
	v_lshlrev_b32_e32 v184, 16, v38
	v_and_b32_e32 v185, 0xffff0000, v38
	v_lshlrev_b32_e32 v186, 16, v39
	v_and_b32_e32 v187, 0xffff0000, v39
	global_load_dwordx4 v[36:39], v[240:241], off offset:2048
	s_waitcnt lgkmcnt(3)
	v_pk_fma_f32 v[112:113], v[180:181], v[232:233], v[112:113]
	v_pk_fma_f32 v[114:115], v[182:183], v[234:235], v[114:115]
	s_waitcnt lgkmcnt(2)
	v_pk_fma_f32 v[116:117], v[184:185], v[236:237], v[116:117]
	v_pk_fma_f32 v[90:91], v[186:187], v[238:239], v[90:91]
	v_pk_fma_f32 v[172:173], v[180:181], v[224:225], v[172:173]
	v_pk_fma_f32 v[174:175], v[182:183], v[226:227], v[174:175]
	v_pk_fma_f32 v[176:177], v[184:185], v[228:229], v[176:177]
	v_pk_fma_f32 v[178:179], v[186:187], v[230:231], v[178:179]
	ds_read_b128 v[224:227], v75 offset:8192
	ds_read_b128 v[228:231], v75 offset:8208
	s_waitcnt vmcnt(15)
	v_lshlrev_b32_e32 v180, 16, v40
	v_and_b32_e32 v181, 0xffff0000, v40
	v_lshlrev_b32_e32 v182, 16, v41
	v_and_b32_e32 v183, 0xffff0000, v41
	v_lshlrev_b32_e32 v184, 16, v42
	v_and_b32_e32 v185, 0xffff0000, v42
	v_lshlrev_b32_e32 v186, 16, v43
	v_and_b32_e32 v187, 0xffff0000, v43
	global_load_dwordx4 v[40:43], v[240:241], off offset:3072
	s_nop 0
	v_lshl_add_u64 v[240:241], v[240:241], 0, s[6:7]
	s_waitcnt lgkmcnt(3)
	v_pk_fma_f32 v[112:113], v[180:181], v[188:189], v[112:113]
	v_pk_fma_f32 v[114:115], v[182:183], v[190:191], v[114:115]
	s_waitcnt lgkmcnt(2)
	v_pk_fma_f32 v[116:117], v[184:185], v[220:221], v[116:117]
	v_pk_fma_f32 v[90:91], v[186:187], v[222:223], v[90:91]
	v_pk_fma_f32 v[172:173], v[180:181], v[232:233], v[172:173]
	v_pk_fma_f32 v[174:175], v[182:183], v[234:235], v[174:175]
	v_pk_fma_f32 v[176:177], v[184:185], v[236:237], v[176:177]
	v_pk_fma_f32 v[178:179], v[186:187], v[238:239], v[178:179]
	ds_read_b128 v[232:235], v75 offset:10240
	ds_read_b128 v[236:239], v75 offset:10256
	s_waitcnt vmcnt(15)
; #define LAS __attribute__((address_space(3)))
; __device__ __forceinline__ void unpack8(u32x4 w, f32x4& a, f32x4& b) { a = (f32x4){bf_lo(w.x), bf_hi(w.x), bf_lo(w.y), bf_hi(w.y)}; b = (f32x4){bf_lo(w.z), bf_hi(w.z), bf_lo(w.w), bf_hi(w.w)}; }
; __device__ __forceinline__ void phase_conv(CParams& p, LAS unsigned char* lds) {
;     ...
;             for (int j = 0; j < 31; ++j) {
;                 unpack8(xr[j + 1], y0, y1);
;                 const f32x4 w0 = *(const LAS f32x4*)(wl + j * 512 + ch0), w1 = *(const LAS f32x4*)(wl + j * 512 + ch0 + 4);
;                 a0 += x0 * w0; a1 += x1 * w1; b0 += y0 * w0; b1 += y1 * w1;
;                 x0 = y0; x1 = y1;
;             }
	v_lshlrev_b32_e32 v180, 16, v44
	v_and_b32_e32 v181, 0xffff0000, v44
	v_lshlrev_b32_e32 v182, 16, v45
	v_and_b32_e32 v183, 0xffff0000, v45
	v_lshlrev_b32_e32 v184, 16, v46
	v_and_b32_e32 v185, 0xffff0000, v46
	v_lshlrev_b32_e32 v186, 16, v47
	v_and_b32_e32 v187, 0xffff0000, v47
	global_load_dwordx4 v[44:47], v[240:241], off offset:0
	s_waitcnt lgkmcnt(3)
	v_pk_fma_f32 v[112:113], v[180:181], v[224:225], v[112:113]
	v_pk_fma_f32 v[114:115], v[182:183], v[226:227], v[114:115]
	s_waitcnt lgkmcnt(2)
	v_pk_fma_f32 v[116:117], v[184:185], v[228:229], v[116:117]
	v_pk_fma_f32 v[90:91], v[186:187], v[230:231], v[90:91]
	v_pk_fma_f32 v[172:173], v[180:181], v[188:189], v[172:173]
	v_pk_fma_f32 v[174:175], v[182:183], v[190:191], v[174:175]
	v_pk_fma_f32 v[176:177], v[184:185], v[220:221], v[176:177]
	v_pk_fma_f32 v[178:179], v[186:187], v[222:223], v[178:179]
	ds_read_b128 v[188:191], v75 offset:12288
	ds_read_b128 v[220:223], v75 offset:12304
	s_waitcnt vmcnt(15)
	v_lshlrev_b32_e32 v180, 16, v48
	v_and_b32_e32 v181, 0xffff0000, v48
	v_lshlrev_b32_e32 v182, 16, v49
	v_and_b32_e32 v183, 0xffff0000, v49
	v_lshlrev_b32_e32 v184, 16, v50
	v_and_b32_e32 v185, 0xffff0000, v50
	v_lshlrev_b32_e32 v186, 16, v51
	v_and_b32_e32 v187, 0xffff0000, v51
	global_load_dwordx4 v[48:51], v[240:241], off offset:1024
	s_waitcnt lgkmcnt(3)
	v_pk_fma_f32 v[112:113], v[180:181], v[232:233], v[112:113]
	v_pk_fma_f32 v[114:115], v[182:183], v[234:235], v[114:115]
	s_waitcnt lgkmcnt(2)
	v_pk_fma_f32 v[116:117], v[184:185], v[236:237], v[116:117]
	v_pk_fma_f32 v[90:91], v[186:187], v[238:239], v[90:91]
	v_pk_fma_f32 v[172:173], v[180:181], v[224:225], v[172:173]
	v_pk_fma_f32 v[174:175], v[182:183], v[226:227], v[174:175]
	v_pk_fma_f32 v[176:177], v[184:185], v[228:229], v[176:177]
	v_pk_fma_f32 v[178:179], v[186:187], v[230:231], v[178:179]
	ds_read_b128 v[224:227], v75 offset:14336
	ds_read_b128 v[228:231], v75 offset:14352
	s_waitcnt vmcnt(15)
	v_lshlrev_b32_e32 v180, 16, v52
	v_and_b32_e32 v181, 0xffff0000, v52
	v_lshlrev_b32_e32 v182, 16, v53
	v_and_b32_e32 v183, 0xffff0000, v53
	v_lshlrev_b32_e32 v184, 16, v54
	v_and_b32_e32 v185, 0xffff0000, v54
	v_lshlrev_b32_e32 v186, 16, v55
	v_and_b32_e32 v187, 0xffff0000, v55
	global_load_dwordx4 v[52:55], v[240:241], off offset:2048
	s_waitcnt lgkmcnt(3)
	v_pk_fma_f32 v[112:113], v[180:181], v[188:189], v[112:113]
	v_pk_fma_f32 v[114:115], v[182:183], v[190:191], v[114:115]
	s_waitcnt lgkmcnt(2)
	v_pk_fma_f32 v[116:117], v[184:185], v[220:221], v[116:117]
	v_pk_fma_f32 v[90:91], v[186:187], v[222:223], v[90:91]
	v_pk_fma_f32 v[172:173], v[180:181], v[232:233], v[172:173]
	v_pk_fma_f32 v[174:175], v[182:183], v[234:235], v[174:175]
	v_pk_fma_f32 v[176:177], v[184:185], v[236:237], v[176:177]
	v_pk_fma_f32 v[178:179], v[186:187], v[238:239], v[178:179]
	ds_read_b128 v[232:235], v75 offset:16384
	ds_read_b128 v[236:239], v75 offset:16400
	s_waitcnt vmcnt(15)
	v_lshlrev_b32_e32 v180, 16, v56
	v_and_b32_e32 v181, 0xffff0000, v56
	v_lshlrev_b32_e32 v182, 16, v57
	v_and_b32_e32 v183, 0xffff0000, v57
	v_lshlrev_b32_e32 v184, 16, v58
	v_and_b32_e32 v185, 0xffff0000, v58
	v_lshlrev_b32_e32 v186, 16, v59
	v_and_b32_e32 v187, 0xffff0000, v59
	global_load_dwordx4 v[56:59], v[240:241], off offset:3072
	s_nop 0
	v_lshl_add_u64 v[240:241], v[240:241], 0, s[6:7]
	s_waitcnt lgkmcnt(3)
	v_pk_fma_f32 v[112:113], v[180:181], v[224:225], v[112:113]
	v_pk_fma_f32 v[114:115], v[182:183], v[226:227], v[114:115]
	s_waitcnt lgkmcnt(2)
	v_pk_fma_f32 v[116:117], v[184:185], v[228:229], v[116:117]
	v_pk_fma_f32 v[90:91], v[186:187], v[230:231], v[90:91]
	v_pk_fma_f32 v[172:173], v[180:181], v[188:189], v[172:173]
	v_pk_fma_f32 v[174:175], v[182:183], v[190:191], v[174:175]
	v_pk_fma_f32 v[176:177], v[184:185], v[220:221], v[176:177]
	v_pk_fma_f32 v[178:179], v[186:187], v[222:223], v[178:179]
	ds_read_b128 v[188:191], v75 offset:18432
	ds_read_b128 v[220:223], v75 offset:18448
	s_waitcnt vmcnt(15)
	v_lshlrev_b32_e32 v180, 16, v60
	v_and_b32_e32 v181, 0xffff0000, v60
	v_lshlrev_b32_e32 v182, 16, v61
	v_and_b32_e32 v183, 0xffff0000, v61
	v_lshlrev_b32_e32 v184, 16, v62
	v_and_b32_e32 v185, 0xffff0000, v62
	v_lshlrev_b32_e32 v186, 16, v63
	v_and_b32_e32 v187, 0xffff0000, v63
	global_load_dwordx4 v[60:63], v[240:241], off offset:0
	s_waitcnt lgkmcnt(3)
	v_pk_fma_f32 v[112:113], v[180:181], v[232:233], v[112:113]
	v_pk_fma_f32 v[114:115], v[182:183], v[234:235], v[114:115]
	s_waitcnt lgkmcnt(2)
	v_pk_fma_f32 v[116:117], v[184:185], v[236:237], v[116:117]
	v_pk_fma_f32 v[90:91], v[186:187], v[238:239], v[90:91]
	v_pk_fma_f32 v[172:173], v[180:181], v[224:225], v[172:173]
	v_pk_fma_f32 v[174:175], v[182:183], v[226:227], v[174:175]
	v_pk_fma_f32 v[176:177], v[184:185], v[228:229], v[176:177]
	v_pk_fma_f32 v[178:179], v[186:187], v[230:231], v[178:179]
	ds_read_b128 v[224:227], v75 offset:20480
	ds_read_b128 v[228:231], v75 offset:20496
	s_waitcnt vmcnt(15)
	v_lshlrev_b32_e32 v180, 16, v80
	v_and_b32_e32 v181, 0xffff0000, v80
	v_lshlrev_b32_e32 v182, 16, v81
	v_and_b32_e32 v183, 0xffff0000, v81
	v_lshlrev_b32_e32 v184, 16, v82
	v_and_b32_e32 v185, 0xffff0000, v82
	v_lshlrev_b32_e32 v186, 16, v83
	v_and_b32_e32 v187, 0xffff0000, v83
	global_load_dwordx4 v[80:83], v[240:241], off offset:1024
	s_waitcnt lgkmcnt(3)
	v_pk_fma_f32 v[112:113], v[180:181], v[188:189], v[112:113]
	v_pk_fma_f32 v[114:115], v[182:183], v[190:191], v[114:115]
	s_waitcnt lgkmcnt(2)
; #define LAS __attribute__((address_space(3)))
; __device__ __forceinline__ void unpack8(u32x4 w, f32x4& a, f32x4& b) { a = (f32x4){bf_lo(w.x), bf_hi(w.x), bf_lo(w.y), bf_hi(w.y)}; b = (f32x4){bf_lo(w.z), bf_hi(w.z), bf_lo(w.w), bf_hi(w.w)}; }
; __device__ __forceinline__ void phase_conv(CParams& p, LAS unsigned char* lds) {
;     ...
;             for (int j = 0; j < 31; ++j) {
;                 unpack8(xr[j + 1], y0, y1);
;                 const f32x4 w0 = *(const LAS f32x4*)(wl + j * 512 + ch0), w1 = *(const LAS f32x4*)(wl + j * 512 + ch0 + 4);
;                 a0 += x0 * w0; a1 += x1 * w1; b0 += y0 * w0; b1 += y1 * w1;
;                 x0 = y0; x1 = y1;
;             }
	v_pk_fma_f32 v[116:117], v[184:185], v[220:221], v[116:117]
	v_pk_fma_f32 v[90:91], v[186:187], v[222:223], v[90:91]
	v_pk_fma_f32 v[172:173], v[180:181], v[232:233], v[172:173]
	v_pk_fma_f32 v[174:175], v[182:183], v[234:235], v[174:175]
	v_pk_fma_f32 v[176:177], v[184:185], v[236:237], v[176:177]
	v_pk_fma_f32 v[178:179], v[186:187], v[238:239], v[178:179]
	ds_read_b128 v[232:235], v75 offset:22528
	ds_read_b128 v[236:239], v75 offset:22544
	s_waitcnt vmcnt(15)
	v_lshlrev_b32_e32 v180, 16, v84
	v_and_b32_e32 v181, 0xffff0000, v84
	v_lshlrev_b32_e32 v182, 16, v85
	v_and_b32_e32 v183, 0xffff0000, v85
	v_lshlrev_b32_e32 v184, 16, v86
	v_and_b32_e32 v185, 0xffff0000, v86
	v_lshlrev_b32_e32 v186, 16, v87
	v_and_b32_e32 v187, 0xffff0000, v87
	global_load_dwordx4 v[84:87], v[240:241], off offset:2048
	s_waitcnt lgkmcnt(3)
	v_pk_fma_f32 v[112:113], v[180:181], v[224:225], v[112:113]
	v_pk_fma_f32 v[114:115], v[182:183], v[226:227], v[114:115]
	s_waitcnt lgkmcnt(2)
	v_pk_fma_f32 v[116:117], v[184:185], v[228:229], v[116:117]
	v_pk_fma_f32 v[90:91], v[186:187], v[230:231], v[90:91]
	v_pk_fma_f32 v[172:173], v[180:181], v[188:189], v[172:173]
	v_pk_fma_f32 v[174:175], v[182:183], v[190:191], v[174:175]
	v_pk_fma_f32 v[176:177], v[184:185], v[220:221], v[176:177]
	v_pk_fma_f32 v[178:179], v[186:187], v[222:223], v[178:179]
	ds_read_b128 v[188:191], v75 offset:24576
	ds_read_b128 v[220:223], v75 offset:24592
	s_waitcnt vmcnt(15)
	v_lshlrev_b32_e32 v180, 16, v92
	v_and_b32_e32 v181, 0xffff0000, v92
	v_lshlrev_b32_e32 v182, 16, v93
	v_and_b32_e32 v183, 0xffff0000, v93
	v_lshlrev_b32_e32 v184, 16, v94
	v_and_b32_e32 v185, 0xffff0000, v94
	v_lshlrev_b32_e32 v186, 16, v95
	v_and_b32_e32 v187, 0xffff0000, v95
	global_load_dwordx4 v[92:95], v[240:241], off offset:3072
	s_nop 0
	v_lshl_add_u64 v[240:241], v[240:241], 0, s[6:7]
	s_waitcnt lgkmcnt(3)
	v_pk_fma_f32 v[112:113], v[180:181], v[232:233], v[112:113]
	v_pk_fma_f32 v[114:115], v[182:183], v[234:235], v[114:115]
	s_waitcnt lgkmcnt(2)
	v_pk_fma_f32 v[116:117], v[184:185], v[236:237], v[116:117]
	v_pk_fma_f32 v[90:91], v[186:187], v[238:239], v[90:91]
	v_pk_fma_f32 v[172:173], v[180:181], v[224:225], v[172:173]
	v_pk_fma_f32 v[174:175], v[182:183], v[226:227], v[174:175]
	v_pk_fma_f32 v[176:177], v[184:185], v[228:229], v[176:177]
	v_pk_fma_f32 v[178:179], v[186:187], v[230:231], v[178:179]
	ds_read_b128 v[224:227], v75 offset:26624
	ds_read_b128 v[228:231], v75 offset:26640
	s_waitcnt vmcnt(15)
	v_lshlrev_b32_e32 v180, 16, v96
	v_and_b32_e32 v181, 0xffff0000, v96
	v_lshlrev_b32_e32 v182, 16, v97
	v_and_b32_e32 v183, 0xffff0000, v97
	v_lshlrev_b32_e32 v184, 16, v98
	v_and_b32_e32 v185, 0xffff0000, v98
	v_lshlrev_b32_e32 v186, 16, v99
	v_and_b32_e32 v187, 0xffff0000, v99
	global_load_dwordx4 v[96:99], v[240:241], off offset:0
	s_waitcnt lgkmcnt(3)
	v_pk_fma_f32 v[112:113], v[180:181], v[188:189], v[112:113]
	v_pk_fma_f32 v[114:115], v[182:183], v[190:191], v[114:115]
	s_waitcnt lgkmcnt(2)
	v_pk_fma_f32 v[116:117], v[184:185], v[220:221], v[116:117]
	v_pk_fma_f32 v[90:91], v[186:187], v[222:223], v[90:91]
	v_pk_fma_f32 v[172:173], v[180:181], v[232:233], v[172:173]
	v_pk_fma_f32 v[174:175], v[182:183], v[234:235], v[174:175]
	v_pk_fma_f32 v[176:177], v[184:185], v[236:237], v[176:177]
	v_pk_fma_f32 v[178:179], v[186:187], v[238:239], v[178:179]
	ds_read_b128 v[232:235], v75 offset:28672
	ds_read_b128 v[236:239], v75 offset:28688
	s_waitcnt vmcnt(15)
	v_lshlrev_b32_e32 v180, 16, v100
	v_and_b32_e32 v181, 0xffff0000, v100
	v_lshlrev_b32_e32 v182, 16, v101
	v_and_b32_e32 v183, 0xffff0000, v101
	v_lshlrev_b32_e32 v184, 16, v102
	v_and_b32_e32 v185, 0xffff0000, v102
	v_lshlrev_b32_e32 v186, 16, v103
	v_and_b32_e32 v187, 0xffff0000, v103
	global_load_dwordx4 v[100:103], v[240:241], off offset:1024
	s_waitcnt lgkmcnt(3)
	v_pk_fma_f32 v[112:113], v[180:181], v[224:225], v[112:113]
	v_pk_fma_f32 v[114:115], v[182:183], v[226:227], v[114:115]
	s_waitcnt lgkmcnt(2)
	v_pk_fma_f32 v[116:117], v[184:185], v[228:229], v[116:117]
	v_pk_fma_f32 v[90:91], v[186:187], v[230:231], v[90:91]
	v_pk_fma_f32 v[172:173], v[180:181], v[188:189], v[172:173]
	v_pk_fma_f32 v[174:175], v[182:183], v[190:191], v[174:175]
	v_pk_fma_f32 v[176:177], v[184:185], v[220:221], v[176:177]
	v_pk_fma_f32 v[178:179], v[186:187], v[222:223], v[178:179]
	ds_read_b128 v[188:191], v75 offset:30720
	ds_read_b128 v[220:223], v75 offset:30736
	s_waitcnt vmcnt(15)
	v_lshlrev_b32_e32 v180, 16, v104
	v_and_b32_e32 v181, 0xffff0000, v104
	v_lshlrev_b32_e32 v182, 16, v105
	v_and_b32_e32 v183, 0xffff0000, v105
	v_lshlrev_b32_e32 v184, 16, v106
	v_and_b32_e32 v185, 0xffff0000, v106
	v_lshlrev_b32_e32 v186, 16, v107
	v_and_b32_e32 v187, 0xffff0000, v107
	global_load_dwordx4 v[104:107], v[240:241], off offset:2048
	s_waitcnt lgkmcnt(3)
	v_pk_fma_f32 v[112:113], v[180:181], v[232:233], v[112:113]
	v_pk_fma_f32 v[114:115], v[182:183], v[234:235], v[114:115]
	s_waitcnt lgkmcnt(2)
	v_pk_fma_f32 v[116:117], v[184:185], v[236:237], v[116:117]
	v_pk_fma_f32 v[90:91], v[186:187], v[238:239], v[90:91]
	v_pk_fma_f32 v[172:173], v[180:181], v[224:225], v[172:173]
	v_pk_fma_f32 v[174:175], v[182:183], v[226:227], v[174:175]
	v_pk_fma_f32 v[176:177], v[184:185], v[228:229], v[176:177]
	v_pk_fma_f32 v[178:179], v[186:187], v[230:231], v[178:179]
	ds_read_b128 v[224:227], v75 offset:32768
	ds_read_b128 v[228:231], v75 offset:32784
	s_waitcnt vmcnt(15)
	v_lshlrev_b32_e32 v180, 16, v108
	v_and_b32_e32 v181, 0xffff0000, v108
	v_lshlrev_b32_e32 v182, 16, v109
	v_and_b32_e32 v183, 0xffff0000, v109
	v_lshlrev_b32_e32 v184, 16, v110
	v_and_b32_e32 v185, 0xffff0000, v110
	v_lshlrev_b32_e32 v186, 16, v111
	v_and_b32_e32 v187, 0xffff0000, v111
	global_load_dwordx4 v[108:111], v[240:241], off offset:3072
	s_nop 0
	v_lshl_add_u64 v[240:241], v[240:241], 0, s[6:7]
	s_waitcnt lgkmcnt(3)
; #define LAS __attribute__((address_space(3)))
; __device__ __forceinline__ void unpack8(u32x4 w, f32x4& a, f32x4& b) { a = (f32x4){bf_lo(w.x), bf_hi(w.x), bf_lo(w.y), bf_hi(w.y)}; b = (f32x4){bf_lo(w.z), bf_hi(w.z), bf_lo(w.w), bf_hi(w.w)}; }
; __device__ __forceinline__ void phase_conv(CParams& p, LAS unsigned char* lds) {
;     ...
;             for (int j = 0; j < 31; ++j) {
;                 unpack8(xr[j + 1], y0, y1);
;                 const f32x4 w0 = *(const LAS f32x4*)(wl + j * 512 + ch0), w1 = *(const LAS f32x4*)(wl + j * 512 + ch0 + 4);
;                 a0 += x0 * w0; a1 += x1 * w1; b0 += y0 * w0; b1 += y1 * w1;
;                 x0 = y0; x1 = y1;
;             }
	v_pk_fma_f32 v[112:113], v[180:181], v[188:189], v[112:113]
	v_pk_fma_f32 v[114:115], v[182:183], v[190:191], v[114:115]
	s_waitcnt lgkmcnt(2)
	v_pk_fma_f32 v[116:117], v[184:185], v[220:221], v[116:117]
	v_pk_fma_f32 v[90:91], v[186:187], v[222:223], v[90:91]
	v_pk_fma_f32 v[172:173], v[180:181], v[232:233], v[172:173]
	v_pk_fma_f32 v[174:175], v[182:183], v[234:235], v[174:175]
	v_pk_fma_f32 v[176:177], v[184:185], v[236:237], v[176:177]
	v_pk_fma_f32 v[178:179], v[186:187], v[238:239], v[178:179]
	ds_read_b128 v[232:235], v75 offset:34816
	ds_read_b128 v[236:239], v75 offset:34832
	s_waitcnt vmcnt(15)
	v_lshlrev_b32_e32 v180, 16, v28
	v_and_b32_e32 v181, 0xffff0000, v28
	v_lshlrev_b32_e32 v182, 16, v29
	v_and_b32_e32 v183, 0xffff0000, v29
	v_lshlrev_b32_e32 v184, 16, v30
	v_and_b32_e32 v185, 0xffff0000, v30
	v_lshlrev_b32_e32 v186, 16, v31
	v_and_b32_e32 v187, 0xffff0000, v31
	s_waitcnt lgkmcnt(3)
	v_pk_fma_f32 v[112:113], v[180:181], v[224:225], v[112:113]
	v_pk_fma_f32 v[114:115], v[182:183], v[226:227], v[114:115]
	s_waitcnt lgkmcnt(2)
	v_pk_fma_f32 v[116:117], v[184:185], v[228:229], v[116:117]
	v_pk_fma_f32 v[90:91], v[186:187], v[230:231], v[90:91]
	v_pk_fma_f32 v[172:173], v[180:181], v[188:189], v[172:173]
	v_pk_fma_f32 v[174:175], v[182:183], v[190:191], v[174:175]
	v_pk_fma_f32 v[176:177], v[184:185], v[220:221], v[176:177]
	v_pk_fma_f32 v[178:179], v[186:187], v[222:223], v[178:179]
	ds_read_b128 v[188:191], v75 offset:36864
	ds_read_b128 v[220:223], v75 offset:36880
	s_waitcnt vmcnt(14)
	v_lshlrev_b32_e32 v180, 16, v32
	v_and_b32_e32 v181, 0xffff0000, v32
	v_lshlrev_b32_e32 v182, 16, v33
	v_and_b32_e32 v183, 0xffff0000, v33
	v_lshlrev_b32_e32 v184, 16, v34
	v_and_b32_e32 v185, 0xffff0000, v34
	v_lshlrev_b32_e32 v186, 16, v35
	v_and_b32_e32 v187, 0xffff0000, v35
	s_waitcnt lgkmcnt(3)
	v_pk_fma_f32 v[112:113], v[180:181], v[232:233], v[112:113]
	v_pk_fma_f32 v[114:115], v[182:183], v[234:235], v[114:115]
	s_waitcnt lgkmcnt(2)
	v_pk_fma_f32 v[116:117], v[184:185], v[236:237], v[116:117]
	v_pk_fma_f32 v[90:91], v[186:187], v[238:239], v[90:91]
	v_pk_fma_f32 v[172:173], v[180:181], v[224:225], v[172:173]
	v_pk_fma_f32 v[174:175], v[182:183], v[226:227], v[174:175]
	v_pk_fma_f32 v[176:177], v[184:185], v[228:229], v[176:177]
	v_pk_fma_f32 v[178:179], v[186:187], v[230:231], v[178:179]
	ds_read_b128 v[224:227], v75 offset:38912
	ds_read_b128 v[228:231], v75 offset:38928
	s_waitcnt vmcnt(13)
	v_lshlrev_b32_e32 v180, 16, v36
	v_and_b32_e32 v181, 0xffff0000, v36
	v_lshlrev_b32_e32 v182, 16, v37
	v_and_b32_e32 v183, 0xffff0000, v37
	v_lshlrev_b32_e32 v184, 16, v38
	v_and_b32_e32 v185, 0xffff0000, v38
	v_lshlrev_b32_e32 v186, 16, v39
	v_and_b32_e32 v187, 0xffff0000, v39
	s_waitcnt lgkmcnt(3)
	v_pk_fma_f32 v[112:113], v[180:181], v[188:189], v[112:113]
	v_pk_fma_f32 v[114:115], v[182:183], v[190:191], v[114:115]
	s_waitcnt lgkmcnt(2)
	v_pk_fma_f32 v[116:117], v[184:185], v[220:221], v[116:117]
	v_pk_fma_f32 v[90:91], v[186:187], v[222:223], v[90:91]
	v_pk_fma_f32 v[172:173], v[180:181], v[232:233], v[172:173]
	v_pk_fma_f32 v[174:175], v[182:183], v[234:235], v[174:175]
	v_pk_fma_f32 v[176:177], v[184:185], v[236:237], v[176:177]
	v_pk_fma_f32 v[178:179], v[186:187], v[238:239], v[178:179]
	ds_read_b128 v[232:235], v75 offset:40960
	ds_read_b128 v[236:239], v75 offset:40976
	s_waitcnt vmcnt(12)
	v_lshlrev_b32_e32 v180, 16, v40
	v_and_b32_e32 v181, 0xffff0000, v40
	v_lshlrev_b32_e32 v182, 16, v41
	v_and_b32_e32 v183, 0xffff0000, v41
	v_lshlrev_b32_e32 v184, 16, v42
	v_and_b32_e32 v185, 0xffff0000, v42
	v_lshlrev_b32_e32 v186, 16, v43
	v_and_b32_e32 v187, 0xffff0000, v43
	s_waitcnt lgkmcnt(3)
	v_pk_fma_f32 v[112:113], v[180:181], v[224:225], v[112:113]
	v_pk_fma_f32 v[114:115], v[182:183], v[226:227], v[114:115]
	s_waitcnt lgkmcnt(2)
	v_pk_fma_f32 v[116:117], v[184:185], v[228:229], v[116:117]
	v_pk_fma_f32 v[90:91], v[186:187], v[230:231], v[90:91]
	v_pk_fma_f32 v[172:173], v[180:181], v[188:189], v[172:173]
	v_pk_fma_f32 v[174:175], v[182:183], v[190:191], v[174:175]
	v_pk_fma_f32 v[176:177], v[184:185], v[220:221], v[176:177]
	v_pk_fma_f32 v[178:179], v[186:187], v[222:223], v[178:179]
	ds_read_b128 v[188:191], v75 offset:43008
	ds_read_b128 v[220:223], v75 offset:43024
	s_waitcnt vmcnt(11)
	v_lshlrev_b32_e32 v180, 16, v44
	v_and_b32_e32 v181, 0xffff0000, v44
	v_lshlrev_b32_e32 v182, 16, v45
	v_and_b32_e32 v183, 0xffff0000, v45
	v_lshlrev_b32_e32 v184, 16, v46
	v_and_b32_e32 v185, 0xffff0000, v46
	v_lshlrev_b32_e32 v186, 16, v47
	v_and_b32_e32 v187, 0xffff0000, v47
	s_waitcnt lgkmcnt(3)
	v_pk_fma_f32 v[112:113], v[180:181], v[232:233], v[112:113]
	v_pk_fma_f32 v[114:115], v[182:183], v[234:235], v[114:115]
	s_waitcnt lgkmcnt(2)
	v_pk_fma_f32 v[116:117], v[184:185], v[236:237], v[116:117]
	v_pk_fma_f32 v[90:91], v[186:187], v[238:239], v[90:91]
	v_pk_fma_f32 v[172:173], v[180:181], v[224:225], v[172:173]
	v_pk_fma_f32 v[174:175], v[182:183], v[226:227], v[174:175]
	v_pk_fma_f32 v[176:177], v[184:185], v[228:229], v[176:177]
	v_pk_fma_f32 v[178:179], v[186:187], v[230:231], v[178:179]
	ds_read_b128 v[224:227], v75 offset:45056
	ds_read_b128 v[228:231], v75 offset:45072
	s_waitcnt vmcnt(10)
	v_lshlrev_b32_e32 v180, 16, v48
	v_and_b32_e32 v181, 0xffff0000, v48
	v_lshlrev_b32_e32 v182, 16, v49
	v_and_b32_e32 v183, 0xffff0000, v49
	v_lshlrev_b32_e32 v184, 16, v50
	v_and_b32_e32 v185, 0xffff0000, v50
	v_lshlrev_b32_e32 v186, 16, v51
	v_and_b32_e32 v187, 0xffff0000, v51
	s_waitcnt lgkmcnt(3)
	v_pk_fma_f32 v[112:113], v[180:181], v[188:189], v[112:113]
	v_pk_fma_f32 v[114:115], v[182:183], v[190:191], v[114:115]
	s_waitcnt lgkmcnt(2)
; #define LAS __attribute__((address_space(3)))
; __device__ __forceinline__ void unpack8(u32x4 w, f32x4& a, f32x4& b) { a = (f32x4){bf_lo(w.x), bf_hi(w.x), bf_lo(w.y), bf_hi(w.y)}; b = (f32x4){bf_lo(w.z), bf_hi(w.z), bf_lo(w.w), bf_hi(w.w)}; }
; __device__ __forceinline__ void phase_conv(CParams& p, LAS unsigned char* lds) {
;     ...
;             for (int j = 0; j < 31; ++j) {
;                 unpack8(xr[j + 1], y0, y1);
;                 const f32x4 w0 = *(const LAS f32x4*)(wl + j * 512 + ch0), w1 = *(const LAS f32x4*)(wl + j * 512 + ch0 + 4);
;                 a0 += x0 * w0; a1 += x1 * w1; b0 += y0 * w0; b1 += y1 * w1;
;                 x0 = y0; x1 = y1;
;             }
	v_pk_fma_f32 v[116:117], v[184:185], v[220:221], v[116:117]
	v_pk_fma_f32 v[90:91], v[186:187], v[222:223], v[90:91]
	v_pk_fma_f32 v[172:173], v[180:181], v[232:233], v[172:173]
	v_pk_fma_f32 v[174:175], v[182:183], v[234:235], v[174:175]
	v_pk_fma_f32 v[176:177], v[184:185], v[236:237], v[176:177]
	v_pk_fma_f32 v[178:179], v[186:187], v[238:239], v[178:179]
	ds_read_b128 v[232:235], v75 offset:47104
	ds_read_b128 v[236:239], v75 offset:47120
	s_waitcnt vmcnt(9)
	v_lshlrev_b32_e32 v180, 16, v52
	v_and_b32_e32 v181, 0xffff0000, v52
	v_lshlrev_b32_e32 v182, 16, v53
	v_and_b32_e32 v183, 0xffff0000, v53
	v_lshlrev_b32_e32 v184, 16, v54
	v_and_b32_e32 v185, 0xffff0000, v54
	v_lshlrev_b32_e32 v186, 16, v55
	v_and_b32_e32 v187, 0xffff0000, v55
	s_waitcnt lgkmcnt(3)
	v_pk_fma_f32 v[112:113], v[180:181], v[224:225], v[112:113]
	v_pk_fma_f32 v[114:115], v[182:183], v[226:227], v[114:115]
	s_waitcnt lgkmcnt(2)
	v_pk_fma_f32 v[116:117], v[184:185], v[228:229], v[116:117]
	v_pk_fma_f32 v[90:91], v[186:187], v[230:231], v[90:91]
	v_pk_fma_f32 v[172:173], v[180:181], v[188:189], v[172:173]
	v_pk_fma_f32 v[174:175], v[182:183], v[190:191], v[174:175]
	v_pk_fma_f32 v[176:177], v[184:185], v[220:221], v[176:177]
	v_pk_fma_f32 v[178:179], v[186:187], v[222:223], v[178:179]
	ds_read_b128 v[188:191], v75 offset:49152
	ds_read_b128 v[220:223], v75 offset:49168
	s_waitcnt vmcnt(8)
	v_lshlrev_b32_e32 v180, 16, v56
	v_and_b32_e32 v181, 0xffff0000, v56
	v_lshlrev_b32_e32 v182, 16, v57
	v_and_b32_e32 v183, 0xffff0000, v57
	v_lshlrev_b32_e32 v184, 16, v58
	v_and_b32_e32 v185, 0xffff0000, v58
	v_lshlrev_b32_e32 v186, 16, v59
	v_and_b32_e32 v187, 0xffff0000, v59
	s_waitcnt lgkmcnt(3)
	v_pk_fma_f32 v[112:113], v[180:181], v[232:233], v[112:113]
	v_pk_fma_f32 v[114:115], v[182:183], v[234:235], v[114:115]
	s_waitcnt lgkmcnt(2)
	v_pk_fma_f32 v[116:117], v[184:185], v[236:237], v[116:117]
	v_pk_fma_f32 v[90:91], v[186:187], v[238:239], v[90:91]
	v_pk_fma_f32 v[172:173], v[180:181], v[224:225], v[172:173]
	v_pk_fma_f32 v[174:175], v[182:183], v[226:227], v[174:175]
	v_pk_fma_f32 v[176:177], v[184:185], v[228:229], v[176:177]
	v_pk_fma_f32 v[178:179], v[186:187], v[230:231], v[178:179]
	ds_read_b128 v[224:227], v75 offset:51200
	ds_read_b128 v[228:231], v75 offset:51216
	s_waitcnt vmcnt(7)
	v_lshlrev_b32_e32 v180, 16, v60
	v_and_b32_e32 v181, 0xffff0000, v60
	v_lshlrev_b32_e32 v182, 16, v61
	v_and_b32_e32 v183, 0xffff0000, v61
	v_lshlrev_b32_e32 v184, 16, v62
	v_and_b32_e32 v185, 0xffff0000, v62
	v_lshlrev_b32_e32 v186, 16, v63
	v_and_b32_e32 v187, 0xffff0000, v63
	s_waitcnt lgkmcnt(3)
	v_pk_fma_f32 v[112:113], v[180:181], v[188:189], v[112:113]
	v_pk_fma_f32 v[114:115], v[182:183], v[190:191], v[114:115]
	s_waitcnt lgkmcnt(2)
	v_pk_fma_f32 v[116:117], v[184:185], v[220:221], v[116:117]
	v_pk_fma_f32 v[90:91], v[186:187], v[222:223], v[90:91]
	v_pk_fma_f32 v[172:173], v[180:181], v[232:233], v[172:173]
	v_pk_fma_f32 v[174:175], v[182:183], v[234:235], v[174:175]
	v_pk_fma_f32 v[176:177], v[184:185], v[236:237], v[176:177]
	v_pk_fma_f32 v[178:179], v[186:187], v[238:239], v[178:179]
	ds_read_b128 v[232:235], v75 offset:53248
	ds_read_b128 v[236:239], v75 offset:53264
	s_waitcnt vmcnt(6)
	v_lshlrev_b32_e32 v180, 16, v80
	v_and_b32_e32 v181, 0xffff0000, v80
	v_lshlrev_b32_e32 v182, 16, v81
	v_and_b32_e32 v183, 0xffff0000, v81
	v_lshlrev_b32_e32 v184, 16, v82
	v_and_b32_e32 v185, 0xffff0000, v82
	v_lshlrev_b32_e32 v186, 16, v83
	v_and_b32_e32 v187, 0xffff0000, v83
	s_waitcnt lgkmcnt(3)
	v_pk_fma_f32 v[112:113], v[180:181], v[224:225], v[112:113]
	v_pk_fma_f32 v[114:115], v[182:183], v[226:227], v[114:115]
	s_waitcnt lgkmcnt(2)
	v_pk_fma_f32 v[116:117], v[184:185], v[228:229], v[116:117]
	v_pk_fma_f32 v[90:91], v[186:187], v[230:231], v[90:91]
	v_pk_fma_f32 v[172:173], v[180:181], v[188:189], v[172:173]
	v_pk_fma_f32 v[174:175], v[182:183], v[190:191], v[174:175]
	v_pk_fma_f32 v[176:177], v[184:185], v[220:221], v[176:177]
	v_pk_fma_f32 v[178:179], v[186:187], v[222:223], v[178:179]
	ds_read_b128 v[188:191], v75 offset:55296
	ds_read_b128 v[220:223], v75 offset:55312
	s_waitcnt vmcnt(5)
	v_lshlrev_b32_e32 v180, 16, v84
	v_and_b32_e32 v181, 0xffff0000, v84
	v_lshlrev_b32_e32 v182, 16, v85
	v_and_b32_e32 v183, 0xffff0000, v85
	v_lshlrev_b32_e32 v184, 16, v86
	v_and_b32_e32 v185, 0xffff0000, v86
	v_lshlrev_b32_e32 v186, 16, v87
	v_and_b32_e32 v187, 0xffff0000, v87
	s_waitcnt lgkmcnt(3)
	v_pk_fma_f32 v[112:113], v[180:181], v[232:233], v[112:113]
	v_pk_fma_f32 v[114:115], v[182:183], v[234:235], v[114:115]
	s_waitcnt lgkmcnt(2)
	v_pk_fma_f32 v[116:117], v[184:185], v[236:237], v[116:117]
	v_pk_fma_f32 v[90:91], v[186:187], v[238:239], v[90:91]
	v_pk_fma_f32 v[172:173], v[180:181], v[224:225], v[172:173]
	v_pk_fma_f32 v[174:175], v[182:183], v[226:227], v[174:175]
	v_pk_fma_f32 v[176:177], v[184:185], v[228:229], v[176:177]
	v_pk_fma_f32 v[178:179], v[186:187], v[230:231], v[178:179]
	ds_read_b128 v[224:227], v75 offset:57344
	ds_read_b128 v[228:231], v75 offset:57360
	s_waitcnt vmcnt(4)
	v_lshlrev_b32_e32 v180, 16, v92
	v_and_b32_e32 v181, 0xffff0000, v92
	v_lshlrev_b32_e32 v182, 16, v93
	v_and_b32_e32 v183, 0xffff0000, v93
	v_lshlrev_b32_e32 v184, 16, v94
	v_and_b32_e32 v185, 0xffff0000, v94
	v_lshlrev_b32_e32 v186, 16, v95
	v_and_b32_e32 v187, 0xffff0000, v95
	s_waitcnt lgkmcnt(3)
	v_pk_fma_f32 v[112:113], v[180:181], v[188:189], v[112:113]
	v_pk_fma_f32 v[114:115], v[182:183], v[190:191], v[114:115]
	s_waitcnt lgkmcnt(2)
; #define LAS __attribute__((address_space(3)))
; __device__ __forceinline__ void unpack8(u32x4 w, f32x4& a, f32x4& b) { a = (f32x4){bf_lo(w.x), bf_hi(w.x), bf_lo(w.y), bf_hi(w.y)}; b = (f32x4){bf_lo(w.z), bf_hi(w.z), bf_lo(w.w), bf_hi(w.w)}; }
; __device__ __forceinline__ void phase_conv(CParams& p, LAS unsigned char* lds) {
;     ...
;         const float mean = wave_sum((c0[0] + c0[1]) + (c0[2] + c0[3]) + (c1[0] + c1[1]) + (c1[2] + c1[3])) * (1.f / 512.f);
;         c0 -= mean; c1 -= mean;
;         const float var = wave_sum(dot4(c0, c0) + dot4(c1, c1)) * (1.f / 512.f);
;     ...
;             for (int j = 0; j < 31; ++j) {
;                 unpack8(xr[j + 1], y0, y1);
;                 const f32x4 w0 = *(const LAS f32x4*)(wl + j * 512 + ch0), w1 = *(const LAS f32x4*)(wl + j * 512 + ch0 + 4);
;                 a0 += x0 * w0; a1 += x1 * w1; b0 += y0 * w0; b1 += y1 * w1;
;                 x0 = y0; x1 = y1;
;             }
;             finish(a0, a1, m); finish(b0, b1, m + 1);
	v_pk_fma_f32 v[116:117], v[184:185], v[220:221], v[116:117]
	v_pk_fma_f32 v[90:91], v[186:187], v[222:223], v[90:91]
	v_pk_fma_f32 v[172:173], v[180:181], v[232:233], v[172:173]
	v_pk_fma_f32 v[174:175], v[182:183], v[234:235], v[174:175]
	v_pk_fma_f32 v[176:177], v[184:185], v[236:237], v[176:177]
	v_pk_fma_f32 v[178:179], v[186:187], v[238:239], v[178:179]
	ds_read_b128 v[232:235], v75 offset:59392
	ds_read_b128 v[236:239], v75 offset:59408
	s_waitcnt vmcnt(3)
	v_lshlrev_b32_e32 v180, 16, v96
	v_and_b32_e32 v181, 0xffff0000, v96
	v_lshlrev_b32_e32 v182, 16, v97
	v_and_b32_e32 v183, 0xffff0000, v97
	v_lshlrev_b32_e32 v184, 16, v98
	v_and_b32_e32 v185, 0xffff0000, v98
	v_lshlrev_b32_e32 v186, 16, v99
	v_and_b32_e32 v187, 0xffff0000, v99
	s_waitcnt lgkmcnt(3)
	v_pk_fma_f32 v[112:113], v[180:181], v[224:225], v[112:113]
	v_pk_fma_f32 v[114:115], v[182:183], v[226:227], v[114:115]
	s_waitcnt lgkmcnt(2)
	v_pk_fma_f32 v[116:117], v[184:185], v[228:229], v[116:117]
	v_pk_fma_f32 v[90:91], v[186:187], v[230:231], v[90:91]
	v_pk_fma_f32 v[172:173], v[180:181], v[188:189], v[172:173]
	v_pk_fma_f32 v[174:175], v[182:183], v[190:191], v[174:175]
	v_pk_fma_f32 v[176:177], v[184:185], v[220:221], v[176:177]
	v_pk_fma_f32 v[178:179], v[186:187], v[222:223], v[178:179]
	ds_read_b128 v[188:191], v75 offset:61440
	ds_read_b128 v[220:223], v75 offset:61456
	s_waitcnt vmcnt(2)
	v_lshlrev_b32_e32 v180, 16, v100
	v_and_b32_e32 v181, 0xffff0000, v100
	v_lshlrev_b32_e32 v182, 16, v101
	v_and_b32_e32 v183, 0xffff0000, v101
	v_lshlrev_b32_e32 v184, 16, v102
	v_and_b32_e32 v185, 0xffff0000, v102
	v_lshlrev_b32_e32 v186, 16, v103
	v_and_b32_e32 v187, 0xffff0000, v103
	s_waitcnt lgkmcnt(3)
	v_pk_fma_f32 v[112:113], v[180:181], v[232:233], v[112:113]
	v_pk_fma_f32 v[114:115], v[182:183], v[234:235], v[114:115]
	s_waitcnt lgkmcnt(2)
	v_pk_fma_f32 v[116:117], v[184:185], v[236:237], v[116:117]
	v_pk_fma_f32 v[90:91], v[186:187], v[238:239], v[90:91]
	v_pk_fma_f32 v[172:173], v[180:181], v[224:225], v[172:173]
	v_pk_fma_f32 v[174:175], v[182:183], v[226:227], v[174:175]
	v_pk_fma_f32 v[176:177], v[184:185], v[228:229], v[176:177]
	v_pk_fma_f32 v[178:179], v[186:187], v[230:231], v[178:179]
	s_waitcnt vmcnt(1)
	v_lshlrev_b32_e32 v180, 16, v104
	v_and_b32_e32 v181, 0xffff0000, v104
	v_lshlrev_b32_e32 v182, 16, v105
	v_and_b32_e32 v183, 0xffff0000, v105
	v_lshlrev_b32_e32 v184, 16, v106
	v_and_b32_e32 v185, 0xffff0000, v106
	v_lshlrev_b32_e32 v186, 16, v107
	v_and_b32_e32 v187, 0xffff0000, v107
	s_waitcnt lgkmcnt(1)
	v_pk_fma_f32 v[112:113], v[180:181], v[188:189], v[112:113]
	v_pk_fma_f32 v[114:115], v[182:183], v[190:191], v[114:115]
	s_waitcnt lgkmcnt(0)
	v_pk_fma_f32 v[116:117], v[184:185], v[220:221], v[116:117]
	v_pk_fma_f32 v[90:91], v[186:187], v[222:223], v[90:91]
	v_pk_fma_f32 v[172:173], v[180:181], v[232:233], v[172:173]
	v_pk_fma_f32 v[174:175], v[182:183], v[234:235], v[174:175]
	v_pk_fma_f32 v[176:177], v[184:185], v[236:237], v[176:177]
	v_pk_fma_f32 v[178:179], v[186:187], v[238:239], v[178:179]
	s_waitcnt vmcnt(0)
	v_lshlrev_b32_e32 v180, 16, v108
	v_and_b32_e32 v181, 0xffff0000, v108
	v_lshlrev_b32_e32 v182, 16, v109
	v_and_b32_e32 v183, 0xffff0000, v109
	v_lshlrev_b32_e32 v184, 16, v110
	v_and_b32_e32 v185, 0xffff0000, v110
	v_lshlrev_b32_e32 v186, 16, v111
	v_and_b32_e32 v187, 0xffff0000, v111
	v_pk_fma_f32 v[172:173], v[180:181], v[188:189], v[172:173]
	v_pk_fma_f32 v[174:175], v[182:183], v[190:191], v[174:175]
	v_pk_fma_f32 v[176:177], v[184:185], v[220:221], v[176:177]
	v_pk_fma_f32 v[178:179], v[186:187], v[222:223], v[178:179]
	v_pk_add_f32 v[28:29], v[112:113], v[114:115]
	v_pk_add_f32 v[30:31], v[116:117], v[90:91]
	s_nop 0
	v_pk_add_f32 v[28:29], v[28:29], v[30:31]
	s_nop 0
	v_add_f32_e32 v32, v28, v29
	s_nop 1
	v_add_f32_dpp v32, v32, v32 quad_perm:[1,0,3,2] row_mask:0xf bank_mask:0xf bound_ctrl:1
	s_nop 1
	v_add_f32_dpp v32, v32, v32 quad_perm:[2,3,0,1] row_mask:0xf bank_mask:0xf bound_ctrl:1
	s_nop 1
	v_add_f32_dpp v32, v32, v32 row_half_mirror row_mask:0xf bank_mask:0xf bound_ctrl:1
	s_nop 1
	v_add_f32_dpp v32, v32, v32 row_mirror row_mask:0xf bank_mask:0xf bound_ctrl:1
	v_mov_b32_e32 v33, v161
	s_nop 1
	v_mov_b32_dpp v33, v32 row_bcast:15 row_mask:0xa bank_mask:0xf
	v_add_f32_e32 v32, v32, v33
	v_mov_b32_e32 v33, v161
	s_nop 1
	v_mov_b32_dpp v33, v32 row_bcast:31 row_mask:0xc bank_mask:0xf
	v_add_f32_e32 v32, v32, v33
	s_nop 0
	v_readlane_b32 s0, v32, 63
	s_nop 1
	v_mul_f32_e32 v28, s0, v204
	s_nop 0
	v_pk_add_f32 v[112:113], v[112:113], v[28:29] op_sel_hi:[1,0]
	v_pk_add_f32 v[114:115], v[114:115], v[28:29] op_sel_hi:[1,0]
	v_pk_add_f32 v[116:117], v[116:117], v[28:29] op_sel_hi:[1,0]
	v_pk_add_f32 v[90:91], v[90:91], v[28:29] op_sel_hi:[1,0]
	v_pk_mul_f32 v[30:31], v[112:113], v[112:113]
	s_nop 0
	v_pk_fma_f32 v[30:31], v[114:115], v[114:115], v[30:31]
	s_nop 0
	v_pk_fma_f32 v[30:31], v[116:117], v[116:117], v[30:31]
	s_nop 0
	v_pk_fma_f32 v[30:31], v[90:91], v[90:91], v[30:31]
	s_nop 0
	v_add_f32_e32 v32, v30, v31
	s_nop 1
	v_add_f32_dpp v32, v32, v32 quad_perm:[1,0,3,2] row_mask:0xf bank_mask:0xf bound_ctrl:1
	s_nop 1
	v_add_f32_dpp v32, v32, v32 quad_perm:[2,3,0,1] row_mask:0xf bank_mask:0xf bound_ctrl:1
	s_nop 1
	v_add_f32_dpp v32, v32, v32 row_half_mirror row_mask:0xf bank_mask:0xf bound_ctrl:1
	s_nop 1
	v_add_f32_dpp v32, v32, v32 row_mirror row_mask:0xf bank_mask:0xf bound_ctrl:1
	v_mov_b32_e32 v33, v161
	s_nop 1
	v_mov_b32_dpp v33, v32 row_bcast:15 row_mask:0xa bank_mask:0xf
	v_add_f32_e32 v32, v32, v33
	v_mov_b32_e32 v33, v161
	s_nop 1
	v_mov_b32_dpp v33, v32 row_bcast:31 row_mask:0xc bank_mask:0xf
	v_add_f32_e32 v32, v32, v33
; __device__ __forceinline__ u32x4 pack8(f32x4 a, f32x4 b) { u32x4 w; w.x = pk2(a[0], a[1]); w.y = pk2(a[2], a[3]); w.z = pk2(b[0], b[1]); w.w = pk2(b[2], b[3]); return w; }
; __device__ __forceinline__ f32x4 sigm4(f32x4 v) { return (f32x4){sigm(v[0]), sigm(v[1]), sigm(v[2]), sigm(v[3])}; }
; __device__ __forceinline__ void phase_conv(CParams& p, LAS unsigned char* lds) {
;     ...
;     auto finish = [&](f32x4 c0, f32x4 c1, int mm) {
;         const float mean = wave_sum((c0[0] + c0[1]) + (c0[2] + c0[3]) + (c1[0] + c1[1]) + (c1[2] + c1[3])) * (1.f / 512.f);
;         c0 -= mean; c1 -= mean;
;         const float var = wave_sum(dot4(c0, c0) + dot4(c1, c1)) * (1.f / 512.f);
;         const float rstd = rsqrtf(var + 1e-5f);
;         c0 = c0 * rstd * lg0 + lb0; c1 = c1 * rstd * lg1 + lb1;
;         *(u32x4*)(p.sconv + (size_t)mm * DCV + ch0) = pack8(c0 * sigm4(c0), c1 * sigm4(c1));
;     };
;     ...
;             finish(a0, a1, m); finish(b0, b1, m + 1);
	s_nop 0
	v_readlane_b32 s0, v32, 63
	s_nop 1
	v_fma_f32 v28, s0, v205, v196
	v_rsq_f32_e32 v28, v28
	s_nop 0
	v_pk_mul_f32 v[112:113], v[112:113], v[28:29] op_sel_hi:[1,0]
	v_pk_mul_f32 v[114:115], v[114:115], v[28:29] op_sel_hi:[1,0]
	v_pk_mul_f32 v[116:117], v[116:117], v[28:29] op_sel_hi:[1,0]
	v_pk_mul_f32 v[90:91], v[90:91], v[28:29] op_sel_hi:[1,0]
	v_pk_fma_f32 v[112:113], v[12:13], v[112:113], v[20:21]
	v_pk_fma_f32 v[114:115], v[14:15], v[114:115], v[22:23]
	v_pk_fma_f32 v[116:117], v[4:5], v[116:117], v[16:17]
	v_pk_fma_f32 v[90:91], v[6:7], v[90:91], v[18:19]
	v_mul_f32_e32 v34, 0xbfb8aa3b, v112
	v_mul_f32_e32 v35, 0xbfb8aa3b, v113
	v_mul_f32_e32 v36, 0xbfb8aa3b, v114
	v_mul_f32_e32 v37, 0xbfb8aa3b, v115
	v_mul_f32_e32 v38, 0xbfb8aa3b, v116
	v_mul_f32_e32 v39, 0xbfb8aa3b, v117
	v_mul_f32_e32 v40, 0xbfb8aa3b, v90
	v_mul_f32_e32 v41, 0xbfb8aa3b, v91
	v_exp_f32_e32 v34, v34
	v_exp_f32_e32 v35, v35
	v_exp_f32_e32 v36, v36
	v_exp_f32_e32 v37, v37
	v_exp_f32_e32 v38, v38
	v_exp_f32_e32 v39, v39
	v_exp_f32_e32 v40, v40
	v_exp_f32_e32 v41, v41
	s_nop 0
	v_pk_add_f32 v[34:35], v[34:35], 1.0 op_sel_hi:[1,0]
	v_pk_add_f32 v[36:37], v[36:37], 1.0 op_sel_hi:[1,0]
	v_pk_add_f32 v[38:39], v[38:39], 1.0 op_sel_hi:[1,0]
	v_pk_add_f32 v[40:41], v[40:41], 1.0 op_sel_hi:[1,0]
	v_rcp_f32_e32 v34, v34
	v_rcp_f32_e32 v35, v35
	v_rcp_f32_e32 v36, v36
	v_rcp_f32_e32 v37, v37
	v_rcp_f32_e32 v38, v38
	v_rcp_f32_e32 v39, v39
	v_rcp_f32_e32 v40, v40
	v_rcp_f32_e32 v41, v41
	s_nop 0
	v_pk_mul_f32 v[112:113], v[112:113], v[34:35]
	v_pk_mul_f32 v[114:115], v[114:115], v[36:37]
	v_pk_mul_f32 v[116:117], v[116:117], v[38:39]
	v_pk_mul_f32 v[90:91], v[90:91], v[40:41]
	v_cvt_pk_bf16_f32 v44, v112, v113
	v_cvt_pk_bf16_f32 v45, v114, v115
	v_cvt_pk_bf16_f32 v46, v116, v117
	v_cvt_pk_bf16_f32 v47, v90, v91
	v_ashrrev_i32_e32 v71, 31, v70
	v_lshlrev_b64 v[242:243], 10, v[70:71]
	v_lshl_add_u64 v[242:243], v[68:69], 0, v[242:243]
	global_store_dwordx4 v[242:243], v[44:47], off
	v_pk_add_f32 v[28:29], v[172:173], v[174:175]
	v_pk_add_f32 v[30:31], v[176:177], v[178:179]
	s_nop 0
	v_pk_add_f32 v[28:29], v[28:29], v[30:31]
	s_nop 0
	v_add_f32_e32 v32, v28, v29
	s_nop 1
	v_add_f32_dpp v32, v32, v32 quad_perm:[1,0,3,2] row_mask:0xf bank_mask:0xf bound_ctrl:1
	s_nop 1
	v_add_f32_dpp v32, v32, v32 quad_perm:[2,3,0,1] row_mask:0xf bank_mask:0xf bound_ctrl:1
	s_nop 1
	v_add_f32_dpp v32, v32, v32 row_half_mirror row_mask:0xf bank_mask:0xf bound_ctrl:1
	s_nop 1
	v_add_f32_dpp v32, v32, v32 row_mirror row_mask:0xf bank_mask:0xf bound_ctrl:1
	v_mov_b32_e32 v33, v161
	s_nop 1
	v_mov_b32_dpp v33, v32 row_bcast:15 row_mask:0xa bank_mask:0xf
	v_add_f32_e32 v32, v32, v33
	v_mov_b32_e32 v33, v161
	s_nop 1
	v_mov_b32_dpp v33, v32 row_bcast:31 row_mask:0xc bank_mask:0xf
	v_add_f32_e32 v32, v32, v33
	s_nop 0
	v_readlane_b32 s0, v32, 63
	s_nop 1
	v_mul_f32_e32 v28, s0, v204
	s_nop 0
	v_pk_add_f32 v[172:173], v[172:173], v[28:29] op_sel_hi:[1,0]
	v_pk_add_f32 v[174:175], v[174:175], v[28:29] op_sel_hi:[1,0]
	v_pk_add_f32 v[176:177], v[176:177], v[28:29] op_sel_hi:[1,0]
	v_pk_add_f32 v[178:179], v[178:179], v[28:29] op_sel_hi:[1,0]
	v_pk_mul_f32 v[30:31], v[172:173], v[172:173]
	s_nop 0
	v_pk_fma_f32 v[30:31], v[174:175], v[174:175], v[30:31]
	s_nop 0
	v_pk_fma_f32 v[30:31], v[176:177], v[176:177], v[30:31]
	s_nop 0
	v_pk_fma_f32 v[30:31], v[178:179], v[178:179], v[30:31]
	s_nop 0
	v_add_f32_e32 v32, v30, v31
	s_nop 1
	v_add_f32_dpp v32, v32, v32 quad_perm:[1,0,3,2] row_mask:0xf bank_mask:0xf bound_ctrl:1
	s_nop 1
	v_add_f32_dpp v32, v32, v32 quad_perm:[2,3,0,1] row_mask:0xf bank_mask:0xf bound_ctrl:1
	s_nop 1
	v_add_f32_dpp v32, v32, v32 row_half_mirror row_mask:0xf bank_mask:0xf bound_ctrl:1
	s_nop 1
	v_add_f32_dpp v32, v32, v32 row_mirror row_mask:0xf bank_mask:0xf bound_ctrl:1
	v_mov_b32_e32 v33, v161
	s_nop 1
	v_mov_b32_dpp v33, v32 row_bcast:15 row_mask:0xa bank_mask:0xf
	v_add_f32_e32 v32, v32, v33
	v_mov_b32_e32 v33, v161
	s_nop 1
	v_mov_b32_dpp v33, v32 row_bcast:31 row_mask:0xc bank_mask:0xf
	v_add_f32_e32 v32, v32, v33
	s_nop 0
	v_readlane_b32 s0, v32, 63
	s_nop 1
	v_fma_f32 v28, s0, v205, v196
	v_rsq_f32_e32 v28, v28
	s_nop 0
	v_pk_mul_f32 v[172:173], v[172:173], v[28:29] op_sel_hi:[1,0]
	v_pk_mul_f32 v[174:175], v[174:175], v[28:29] op_sel_hi:[1,0]
	v_pk_mul_f32 v[176:177], v[176:177], v[28:29] op_sel_hi:[1,0]
	v_pk_mul_f32 v[178:179], v[178:179], v[28:29] op_sel_hi:[1,0]
	v_pk_fma_f32 v[172:173], v[12:13], v[172:173], v[20:21]
	v_pk_fma_f32 v[174:175], v[14:15], v[174:175], v[22:23]
	v_pk_fma_f32 v[176:177], v[4:5], v[176:177], v[16:17]
	v_pk_fma_f32 v[178:179], v[6:7], v[178:179], v[18:19]
	v_mul_f32_e32 v34, 0xbfb8aa3b, v172
	v_mul_f32_e32 v35, 0xbfb8aa3b, v173
	v_mul_f32_e32 v36, 0xbfb8aa3b, v174
	v_mul_f32_e32 v37, 0xbfb8aa3b, v175
	v_mul_f32_e32 v38, 0xbfb8aa3b, v176
	v_mul_f32_e32 v39, 0xbfb8aa3b, v177
	v_mul_f32_e32 v40, 0xbfb8aa3b, v178
	v_mul_f32_e32 v41, 0xbfb8aa3b, v179
	v_exp_f32_e32 v34, v34
	v_exp_f32_e32 v35, v35
	v_exp_f32_e32 v36, v36
	v_exp_f32_e32 v37, v37
	v_exp_f32_e32 v38, v38
	v_exp_f32_e32 v39, v39
	v_exp_f32_e32 v40, v40
	v_exp_f32_e32 v41, v41
	s_nop 0
	v_pk_add_f32 v[34:35], v[34:35], 1.0 op_sel_hi:[1,0]
	v_pk_add_f32 v[36:37], v[36:37], 1.0 op_sel_hi:[1,0]
	v_pk_add_f32 v[38:39], v[38:39], 1.0 op_sel_hi:[1,0]
	v_pk_add_f32 v[40:41], v[40:41], 1.0 op_sel_hi:[1,0]
	v_rcp_f32_e32 v34, v34
	v_rcp_f32_e32 v35, v35
	v_rcp_f32_e32 v36, v36
	v_rcp_f32_e32 v37, v37
	v_rcp_f32_e32 v38, v38
	v_rcp_f32_e32 v39, v39
	v_rcp_f32_e32 v40, v40
	v_rcp_f32_e32 v41, v41
	s_nop 0
	v_pk_mul_f32 v[172:173], v[172:173], v[34:35]
	v_pk_mul_f32 v[174:175], v[174:175], v[36:37]
	v_pk_mul_f32 v[176:177], v[176:177], v[38:39]
	v_pk_mul_f32 v[178:179], v[178:179], v[40:41]
	v_cvt_pk_bf16_f32 v24, v172, v173
	v_cvt_pk_bf16_f32 v25, v174, v175
	v_cvt_pk_bf16_f32 v26, v176, v177
	v_cvt_pk_bf16_f32 v27, v178, v179
	v_or_b32_e32 v72, 1, v70
	s_branch .LBB0_207

; __device__ __forceinline__ void gemm_phase(LAS unsigned char* lds, CParams& p, const Job& jb) {
;     ...
; #pragma unroll
;         for (int a = 0; a < 2; ++a)
; #pragma unroll
;             for (int b = 0; b < 2; ++b)
; #pragma unroll
;                 for (int m = 0; m < 4; ++m)
; #pragma unroll
;                     for (int n = 0; n < 2; ++n) acc[a][b][m][n] = (f32x4){0.f, 0.f, 0.f, 0.f};
;         cur = nxt; cA = nA; cB = nB; ++ui;
.LBB0_601:
	v_mov_b64_e32 v[0:1], 0
	v_mov_b64_e32 v[2:3], 0
	v_mov_b64_e32 v[4:5], 0
	v_mov_b64_e32 v[6:7], 0
	v_mov_b64_e32 v[8:9], 0
	v_mov_b64_e32 v[10:11], 0
	v_mov_b64_e32 v[12:13], 0
	v_mov_b64_e32 v[14:15], 0
	v_mov_b64_e32 v[16:17], 0
	v_mov_b64_e32 v[18:19], 0
	v_mov_b64_e32 v[20:21], 0
	v_mov_b64_e32 v[22:23], 0
	v_mov_b64_e32 v[24:25], 0
	v_mov_b64_e32 v[26:27], 0
	v_mov_b64_e32 v[28:29], 0
	v_mov_b64_e32 v[30:31], 0
	v_mov_b64_e32 v[32:33], 0
	v_mov_b64_e32 v[34:35], 0
	v_mov_b64_e32 v[36:37], 0
	v_mov_b64_e32 v[38:39], 0
	v_mov_b64_e32 v[40:41], 0
	v_mov_b64_e32 v[42:43], 0
	v_mov_b64_e32 v[44:45], 0
	v_mov_b64_e32 v[46:47], 0
	v_mov_b64_e32 v[48:49], 0
	v_mov_b64_e32 v[50:51], 0
	v_mov_b64_e32 v[52:53], 0
	v_mov_b64_e32 v[54:55], 0
	v_mov_b64_e32 v[56:57], 0
	v_mov_b64_e32 v[58:59], 0
	v_mov_b64_e32 v[60:61], 0
	v_mov_b64_e32 v[62:63], 0
	v_mov_b64_e32 v[64:65], 0
	v_mov_b64_e32 v[66:67], 0
	v_mov_b64_e32 v[68:69], 0
	v_mov_b64_e32 v[70:71], 0
	v_mov_b64_e32 v[72:73], 0
	v_mov_b64_e32 v[74:75], 0
	v_mov_b64_e32 v[76:77], 0
	v_mov_b64_e32 v[78:79], 0
	v_mov_b64_e32 v[80:81], 0
	v_mov_b64_e32 v[82:83], 0
	v_mov_b64_e32 v[84:85], 0
	v_mov_b64_e32 v[86:87], 0
	v_mov_b64_e32 v[88:89], 0
	v_mov_b64_e32 v[90:91], 0
	v_mov_b64_e32 v[92:93], 0
	v_mov_b64_e32 v[94:95], 0
	v_mov_b64_e32 v[96:97], 0
	v_mov_b64_e32 v[98:99], 0
	v_mov_b64_e32 v[100:101], 0
	v_mov_b64_e32 v[102:103], 0
	v_mov_b64_e32 v[104:105], 0
	v_mov_b64_e32 v[106:107], 0
	v_mov_b64_e32 v[108:109], 0
	v_mov_b64_e32 v[110:111], 0
	v_mov_b64_e32 v[112:113], 0
	v_mov_b64_e32 v[114:115], 0
	v_mov_b64_e32 v[116:117], 0
	v_mov_b64_e32 v[118:119], 0
	v_mov_b64_e32 v[120:121], 0
	v_mov_b64_e32 v[122:123], 0
	v_mov_b64_e32 v[124:125], 0
	v_mov_b64_e32 v[126:127], 0
	s_mov_b32 s3, s35
	s_mov_b32 s95, s34
	s_mov_b32 s92, s62
	s_mov_b32 s78, s96
	s_mov_b64 s[24:25], s[4:5]
	s_mov_b32 s30, s63
	s_andn2_b64 vcc, exec, s[6:7]
	s_mov_b64 s[10:11], s[86:87]
	s_cbranch_vccz .LBB0_913

; __device__ __forceinline__ u32x4 pack8(f32x4 a, f32x4 b) { u32x4 w; w.x = pk2(a[0], a[1]); w.y = pk2(a[2], a[3]); w.z = pk2(b[0], b[1]); w.w = pk2(b[2], b[3]); return w; }
; __device__ __forceinline__ f32x4 sigm4(f32x4 v) { return (f32x4){sigm(v[0]), sigm(v[1]), sigm(v[2]), sigm(v[3])}; }
; #define FOR_ROWS _Pragma("unroll") for (int ai = 0; ai < 2; ++ai) _Pragma("unroll") for (int m = 0; m < 4; ++m)
; __device__ __forceinline__ void epilogue(const int kind, CParams& p, const f32x4 (&acc)[2][2][4][2], const Unit& u, const int wr, const int wc, const int fr_in, const int fq_in) {
;     ...
;     case E_FFN1: {
;         float rsv[2][4];
;         FOR_ROWS { ROWDEF rsv[ai][m] = p.ss2[row]; }
;         FOR_ROWS { ROWDEF
;             const float rs = rsqrtf(rsv[ai][m] * (1.f / 1024.f) + 1e-6f);
;             const f32x4 g0 = acc[ai][0][m][0] * rs, g1 = acc[ai][0][m][1] * rs, u0 = acc[ai][1][m][0] * rs, u1 = acc[ai][1][m][1] * rs;
;             *(u32x4*)(p.hid + row * DFF + u.pn * 128 + cw) = pack8(g0 * sigm4(g0) * u0, g1 * sigm4(g1) * u1);
;         }
;     } break;
.LBB0_642:
	s_cmp_gt_i32 s3, 11
	s_mov_b64 s[26:27], -1
	s_cbranch_scc0 .LBB0_644
	s_ashr_i32 s79, s78, 31
	v_readlane_b32 s12, v244, 20
	s_lshl_b64 s[10:11], s[78:79], 2
	v_readlane_b32 s18, v244, 26
	v_add_u32_e32 v130, s0, v215
	v_readlane_b32 s19, v244, 27
	s_add_u32 s10, s18, s10
	s_addc_u32 s11, s19, s11
	v_ashrrev_i32_e32 v131, 31, v130
	v_lshl_add_u64 v[128:129], v[130:131], 2, s[10:11]
	global_load_dword v146, v[128:129], off
	v_add_u32_e32 v144, 16, v130
	v_ashrrev_i32_e32 v145, 31, v144
	v_add_u32_e32 v142, 32, v130
	v_lshl_add_u64 v[128:129], v[144:145], 2, s[10:11]
	v_ashrrev_i32_e32 v143, 31, v142
	v_add_u32_e32 v140, 48, v130
	global_load_dword v184, v[128:129], off
	v_lshl_add_u64 v[128:129], v[142:143], 2, s[10:11]
	v_ashrrev_i32_e32 v141, 31, v140
	v_add_u32_e32 v138, 0x80, v130
	global_load_dword v183, v[128:129], off
	v_lshl_add_u64 v[128:129], v[140:141], 2, s[10:11]
	v_ashrrev_i32_e32 v139, 31, v138
	v_add_u32_e32 v136, 0x90, v130
	global_load_dword v182, v[128:129], off
	v_lshl_add_u64 v[128:129], v[138:139], 2, s[10:11]
	v_ashrrev_i32_e32 v137, 31, v136
	v_add_u32_e32 v134, 0xa0, v130
	global_load_dword v181, v[128:129], off
	v_lshl_add_u64 v[128:129], v[136:137], 2, s[10:11]
	v_ashrrev_i32_e32 v135, 31, v134
	global_load_dword v180, v[128:129], off
	v_lshl_add_u64 v[128:129], v[134:135], 2, s[10:11]
	global_load_dword v179, v[128:129], off
	v_add_u32_e32 v128, 0xb0, v130
	v_ashrrev_i32_e32 v129, 31, v128
	v_lshl_add_u64 v[132:133], v[128:129], 2, s[10:11]
	global_load_dword v178, v[132:133], off
	v_lshl_add_u64 v[132:133], v[130:131], 0, s[78:79]
	s_mov_b32 s1, 0x800000
	v_readlane_b32 s14, v244, 22
	s_movk_i32 s14, 0x1600
	v_ashrrev_i32_e32 v173, 31, v172
	v_readlane_b32 s13, v244, 21
	v_lshl_add_u64 v[144:145], v[144:145], 0, s[78:79]
	v_lshl_add_u64 v[142:143], v[142:143], 0, s[78:79]
	v_lshl_add_u64 v[140:141], v[140:141], 0, s[78:79]
	v_lshl_add_u64 v[138:139], v[138:139], 0, s[78:79]
	v_lshl_add_u64 v[136:137], v[136:137], 0, s[78:79]
	v_lshl_add_u64 v[134:135], v[134:135], 0, s[78:79]
	v_lshl_add_u64 v[128:129], v[128:129], 0, s[78:79]
	v_readlane_b32 s15, v244, 23
	v_readlane_b32 s16, v244, 24
	v_readlane_b32 s17, v244, 25
	s_mov_b64 s[26:27], 0
	s_waitcnt vmcnt(0)
	v_fmamk_f32 v130, v146, 0x3a800000, v193
	v_cmp_gt_f32_e32 vcc, s1, v130
	v_mul_f32_e32 v131, 0x4b800000, v130
	s_nop 0
	v_cndmask_b32_e32 v130, v130, v131, vcc
	v_rsq_f32_e32 v130, v130
	s_nop 0
	v_mul_f32_e32 v131, 0x45800000, v130
	v_cndmask_b32_e32 v150, v130, v131, vcc
	v_pk_mul_f32 v[152:153], v[126:127], v[150:151] op_sel_hi:[1,0]
	v_pk_mul_f32 v[154:155], v[124:125], v[150:151] op_sel_hi:[1,0]
	v_mul_f32_e32 v176, 0xbfb8aa3b, v152
	v_mul_f32_e32 v177, 0xbfb8aa3b, v153
	v_exp_f32_e32 v176, v176
	v_exp_f32_e32 v177, v177
	v_mul_f32_e32 v174, 0xbfb8aa3b, v154
	v_mul_f32_e32 v175, 0xbfb8aa3b, v155
	v_exp_f32_e32 v174, v174
	v_pk_add_f32 v[176:177], v[176:177], 1.0 op_sel_hi:[1,0]
	v_exp_f32_e32 v175, v175
	s_nop 0
	v_pk_add_f32 v[174:175], v[174:175], 1.0 op_sel_hi:[1,0]
	v_pk_mul_f32 v[130:131], v[122:123], v[150:151] op_sel_hi:[1,0]
	v_pk_mul_f32 v[158:159], v[94:95], v[150:151] op_sel_hi:[1,0]
	v_rcp_f32_e32 v177, v177
	v_pk_mul_f32 v[146:147], v[120:121], v[150:151] op_sel_hi:[1,0]
	v_pk_mul_f32 v[156:157], v[92:93], v[150:151] op_sel_hi:[1,0]
	v_pk_mul_f32 v[148:149], v[88:89], v[150:151] op_sel_hi:[1,0]
	v_rcp_f32_e32 v176, v176
	s_nop 0
	v_pk_mul_f32 v[152:153], v[152:153], v[176:177]
	v_pk_mul_f32 v[150:151], v[90:91], v[150:151] op_sel_hi:[1,0]
	v_pk_mul_f32 v[152:153], v[158:159], v[152:153]
	v_rcp_f32_e32 v175, v175
	v_mul_f32_e32 v158, 0xbfb8aa3b, v130
	v_mul_f32_e32 v159, 0xbfb8aa3b, v131
	v_exp_f32_e32 v158, v158
	v_exp_f32_e32 v159, v159
	v_rcp_f32_e32 v174, v174
	v_pk_add_f32 v[158:159], v[158:159], 1.0 op_sel_hi:[1,0]
	v_pk_mul_f32 v[154:155], v[154:155], v[174:175]
	s_nop 0
	v_pk_mul_f32 v[154:155], v[156:157], v[154:155]
	v_mul_f32_e32 v156, 0xbfb8aa3b, v146
	v_mul_f32_e32 v157, 0xbfb8aa3b, v147
	v_rcp_f32_e32 v159, v159
	v_exp_f32_e32 v156, v156
	v_exp_f32_e32 v157, v157
	s_nop 0
	v_pk_add_f32 v[156:157], v[156:157], 1.0 op_sel_hi:[1,0]
	v_rcp_f32_e32 v158, v158
	s_nop 0
	v_pk_mul_f32 v[130:131], v[130:131], v[158:159]
	v_rcp_f32_e32 v157, v157
	v_pk_mul_f32 v[130:131], v[150:151], v[130:131]
	v_rcp_f32_e32 v156, v156
	s_nop 0
	v_pk_mul_f32 v[146:147], v[146:147], v[156:157]
	s_nop 0
	v_pk_mul_f32 v[148:149], v[148:149], v[146:147]
	v_cvt_pk_bf16_f32 v146, v154, v155
	v_cvt_pk_bf16_f32 v147, v152, v153
	s_nop 0
	v_cvt_pk_bf16_f32 v148, v148, v149
	v_cvt_pk_bf16_f32 v149, v130, v131
	v_mov_b64_e32 v[130:131], s[40:41]
	v_mad_u64_u32 v[150:151], s[10:11], v132, s14, v[130:131]
	s_lshl_b32 s10, s92, 7
	s_ashr_i32 s11, s10, 31
	v_mad_i32_i24 v151, v133, s14, v151
	s_lshl_b64 s[10:11], s[10:11], 1
	v_lshl_add_u64 v[150:151], v[150:151], 0, s[10:11]
	v_lshlrev_b64 v[132:133], 1, v[172:173]
	v_lshl_add_u64 v[150:151], v[150:151], 0, v[132:133]
	global_store_dwordx4 v[150:151], v[146:149], off
	s_nop 1
	v_fmamk_f32 v146, v184, 0x3a800000, v193
	v_cmp_gt_f32_e32 vcc, s1, v146
	v_mul_f32_e32 v147, 0x4b800000, v146
	s_nop 0
	v_cndmask_b32_e32 v146, v146, v147, vcc
	v_rsq_f32_e32 v146, v146
	s_nop 0
	v_mul_f32_e32 v147, 0x45800000, v146
	v_cndmask_b32_e32 v152, v146, v147, vcc
	v_pk_mul_f32 v[156:157], v[116:117], v[152:153] op_sel_hi:[1,0]
	v_pk_mul_f32 v[154:155], v[118:119], v[152:153] op_sel_hi:[1,0]
	v_mul_f32_e32 v173, 0xbfb8aa3b, v156
	v_exp_f32_e32 v176, v173
	v_mul_f32_e32 v173, 0xbfb8aa3b, v157
	v_exp_f32_e32 v177, v173
	v_mul_f32_e32 v173, 0xbfb8aa3b, v154
	v_exp_f32_e32 v184, v173
	v_mul_f32_e32 v173, 0xbfb8aa3b, v155
; __device__ __forceinline__ u32x4 pack8(f32x4 a, f32x4 b) { u32x4 w; w.x = pk2(a[0], a[1]); w.y = pk2(a[2], a[3]); w.z = pk2(b[0], b[1]); w.w = pk2(b[2], b[3]); return w; }
; __device__ __forceinline__ f32x4 sigm4(f32x4 v) { return (f32x4){sigm(v[0]), sigm(v[1]), sigm(v[2]), sigm(v[3])}; }
; #define FOR_ROWS _Pragma("unroll") for (int ai = 0; ai < 2; ++ai) _Pragma("unroll") for (int m = 0; m < 4; ++m)
; __device__ __forceinline__ void epilogue(const int kind, CParams& p, const f32x4 (&acc)[2][2][4][2], const Unit& u, const int wr, const int wc, const int fr_in, const int fq_in) {
;     ...
;     case E_FFN1: {
;         float rsv[2][4];
;         FOR_ROWS { ROWDEF rsv[ai][m] = p.ss2[row]; }
;         FOR_ROWS { ROWDEF
;             const float rs = rsqrtf(rsv[ai][m] * (1.f / 1024.f) + 1e-6f);
;             const f32x4 g0 = acc[ai][0][m][0] * rs, g1 = acc[ai][0][m][1] * rs, u0 = acc[ai][1][m][0] * rs, u1 = acc[ai][1][m][1] * rs;
;             *(u32x4*)(p.hid + row * DFF + u.pn * 128 + cw) = pack8(g0 * sigm4(g0) * u0, g1 * sigm4(g1) * u1);
;         }
;     } break;
	v_exp_f32_e32 v185, v173
	v_pk_add_f32 v[176:177], v[176:177], 1.0 op_sel_hi:[1,0]
	v_pk_mul_f32 v[146:147], v[114:115], v[152:153] op_sel_hi:[1,0]
	v_pk_mul_f32 v[174:175], v[86:87], v[152:153] op_sel_hi:[1,0]
	v_pk_add_f32 v[184:185], v[184:185], 1.0 op_sel_hi:[1,0]
	v_pk_mul_f32 v[148:149], v[112:113], v[152:153] op_sel_hi:[1,0]
	v_pk_mul_f32 v[158:159], v[84:85], v[152:153] op_sel_hi:[1,0]
	v_pk_mul_f32 v[150:151], v[80:81], v[152:153] op_sel_hi:[1,0]
	v_pk_mul_f32 v[152:153], v[82:83], v[152:153] op_sel_hi:[1,0]
	v_rcp_f32_e32 v185, v185
	s_nop 0
	v_rcp_f32_e32 v184, v184
	s_nop 0
	v_pk_mul_f32 v[154:155], v[154:155], v[184:185]
	v_rcp_f32_e32 v177, v177
	v_pk_mul_f32 v[154:155], v[174:175], v[154:155]
	v_rcp_f32_e32 v176, v176
	v_mul_f32_e32 v173, 0xbfb8aa3b, v146
	v_exp_f32_e32 v174, v173
	v_mul_f32_e32 v173, 0xbfb8aa3b, v147
	v_exp_f32_e32 v175, v173
	v_pk_mul_f32 v[156:157], v[156:157], v[176:177]
	v_pk_add_f32 v[174:175], v[174:175], 1.0 op_sel_hi:[1,0]
	s_nop 0
	v_pk_mul_f32 v[156:157], v[158:159], v[156:157]
	v_mul_f32_e32 v158, 0xbfb8aa3b, v148
	v_mul_f32_e32 v159, 0xbfb8aa3b, v149
	v_rcp_f32_e32 v175, v175
	v_exp_f32_e32 v158, v158
	v_exp_f32_e32 v159, v159
	s_nop 0
	v_pk_add_f32 v[158:159], v[158:159], 1.0 op_sel_hi:[1,0]
	v_rcp_f32_e32 v174, v174
	s_nop 0
	v_pk_mul_f32 v[146:147], v[146:147], v[174:175]
	v_rcp_f32_e32 v159, v159
	v_pk_mul_f32 v[152:153], v[152:153], v[146:147]
	v_cvt_pk_bf16_f32 v146, v156, v157
	v_cvt_pk_bf16_f32 v147, v154, v155
	v_rcp_f32_e32 v158, v158
	s_nop 0
	v_pk_mul_f32 v[148:149], v[148:149], v[158:159]
	s_nop 0
	v_pk_mul_f32 v[148:149], v[150:151], v[148:149]
	v_mad_u64_u32 v[150:151], s[12:13], v144, s14, v[130:131]
	v_mad_i32_i24 v151, v145, s14, v151
	v_lshl_add_u64 v[144:145], v[150:151], 0, s[10:11]
	v_lshl_add_u64 v[144:145], v[144:145], 0, v[132:133]
	v_cvt_pk_bf16_f32 v148, v148, v149
	v_cvt_pk_bf16_f32 v149, v152, v153
	global_store_dwordx4 v[144:145], v[146:149], off
	v_fmamk_f32 v144, v183, 0x3a800000, v193
	v_cmp_gt_f32_e32 vcc, s1, v144
	v_mul_f32_e32 v145, 0x4b800000, v144
	s_nop 0
	v_cndmask_b32_e32 v144, v144, v145, vcc
	v_rsq_f32_e32 v144, v144
	s_nop 0
	v_mul_f32_e32 v145, 0x45800000, v144
	v_cndmask_b32_e32 v150, v144, v145, vcc
	v_pk_mul_f32 v[154:155], v[108:109], v[150:151] op_sel_hi:[1,0]
	v_pk_mul_f32 v[152:153], v[110:111], v[150:151] op_sel_hi:[1,0]
	v_mul_f32_e32 v173, 0xbfb8aa3b, v154
	v_exp_f32_e32 v174, v173
	v_mul_f32_e32 v173, 0xbfb8aa3b, v155
	v_exp_f32_e32 v175, v173
	v_mul_f32_e32 v173, 0xbfb8aa3b, v152
	v_exp_f32_e32 v176, v173
	v_mul_f32_e32 v173, 0xbfb8aa3b, v153
	v_exp_f32_e32 v177, v173
	v_pk_add_f32 v[174:175], v[174:175], 1.0 op_sel_hi:[1,0]
	v_pk_mul_f32 v[144:145], v[106:107], v[150:151] op_sel_hi:[1,0]
	v_pk_mul_f32 v[158:159], v[78:79], v[150:151] op_sel_hi:[1,0]
	v_pk_add_f32 v[176:177], v[176:177], 1.0 op_sel_hi:[1,0]
	v_pk_mul_f32 v[146:147], v[104:105], v[150:151] op_sel_hi:[1,0]
	v_pk_mul_f32 v[156:157], v[76:77], v[150:151] op_sel_hi:[1,0]
	v_pk_mul_f32 v[148:149], v[72:73], v[150:151] op_sel_hi:[1,0]
	v_pk_mul_f32 v[150:151], v[74:75], v[150:151] op_sel_hi:[1,0]
	v_rcp_f32_e32 v177, v177
	s_nop 0
	v_rcp_f32_e32 v176, v176
	s_nop 0
	v_pk_mul_f32 v[152:153], v[152:153], v[176:177]
	v_rcp_f32_e32 v175, v175
	v_pk_mul_f32 v[152:153], v[158:159], v[152:153]
	v_mul_f32_e32 v158, 0xbfb8aa3b, v144
	v_mul_f32_e32 v159, 0xbfb8aa3b, v145
	v_exp_f32_e32 v158, v158
	v_exp_f32_e32 v159, v159
	s_nop 0
	v_pk_add_f32 v[158:159], v[158:159], 1.0 op_sel_hi:[1,0]
	v_rcp_f32_e32 v174, v174
	s_nop 0
	v_pk_mul_f32 v[154:155], v[154:155], v[174:175]
	s_nop 0
	v_pk_mul_f32 v[154:155], v[156:157], v[154:155]
	v_mul_f32_e32 v156, 0xbfb8aa3b, v146
	v_mul_f32_e32 v157, 0xbfb8aa3b, v147
	v_rcp_f32_e32 v159, v159
	v_exp_f32_e32 v156, v156
	v_exp_f32_e32 v157, v157
	s_nop 0
	v_pk_add_f32 v[156:157], v[156:157], 1.0 op_sel_hi:[1,0]
	v_rcp_f32_e32 v158, v158
	s_nop 0
	v_pk_mul_f32 v[144:145], v[144:145], v[158:159]
	v_rcp_f32_e32 v157, v157
	v_pk_mul_f32 v[150:151], v[150:151], v[144:145]
	v_cvt_pk_bf16_f32 v144, v154, v155
	v_cvt_pk_bf16_f32 v145, v152, v153
	v_rcp_f32_e32 v156, v156
	s_nop 0
	v_pk_mul_f32 v[146:147], v[146:147], v[156:157]
	s_nop 0
	v_pk_mul_f32 v[146:147], v[148:149], v[146:147]
	v_mad_u64_u32 v[148:149], s[12:13], v142, s14, v[130:131]
	v_mad_i32_i24 v149, v143, s14, v149
	v_lshl_add_u64 v[142:143], v[148:149], 0, s[10:11]
	v_lshl_add_u64 v[142:143], v[142:143], 0, v[132:133]
	v_cvt_pk_bf16_f32 v146, v146, v147
	v_cvt_pk_bf16_f32 v147, v150, v151
	global_store_dwordx4 v[142:143], v[144:147], off
	v_fmamk_f32 v142, v182, 0x3a800000, v193
	v_cmp_gt_f32_e32 vcc, s1, v142
	v_mul_f32_e32 v143, 0x4b800000, v142
	s_nop 0
	v_cndmask_b32_e32 v142, v142, v143, vcc
	v_rsq_f32_e32 v142, v142
	s_nop 0
	v_mul_f32_e32 v143, 0x45800000, v142
	v_cndmask_b32_e32 v148, v142, v143, vcc
	v_pk_mul_f32 v[150:151], v[102:103], v[148:149] op_sel_hi:[1,0]
	v_pk_mul_f32 v[152:153], v[100:101], v[148:149] op_sel_hi:[1,0]
	v_mul_f32_e32 v173, 0xbfb8aa3b, v150
	v_exp_f32_e32 v174, v173
	v_mul_f32_e32 v173, 0xbfb8aa3b, v151
	v_exp_f32_e32 v175, v173
	v_mul_f32_e32 v158, 0xbfb8aa3b, v152
	v_mul_f32_e32 v159, 0xbfb8aa3b, v153
	v_exp_f32_e32 v158, v158
	v_pk_add_f32 v[174:175], v[174:175], 1.0 op_sel_hi:[1,0]
	v_exp_f32_e32 v159, v159
	s_nop 0
	v_pk_add_f32 v[158:159], v[158:159], 1.0 op_sel_hi:[1,0]
	v_pk_mul_f32 v[142:143], v[98:99], v[148:149] op_sel_hi:[1,0]
	v_pk_mul_f32 v[156:157], v[70:71], v[148:149] op_sel_hi:[1,0]
	v_rcp_f32_e32 v175, v175
	v_pk_mul_f32 v[144:145], v[96:97], v[148:149] op_sel_hi:[1,0]
	v_pk_mul_f32 v[154:155], v[68:69], v[148:149] op_sel_hi:[1,0]
; __device__ __forceinline__ u32x4 pack8(f32x4 a, f32x4 b) { u32x4 w; w.x = pk2(a[0], a[1]); w.y = pk2(a[2], a[3]); w.z = pk2(b[0], b[1]); w.w = pk2(b[2], b[3]); return w; }
; __device__ __forceinline__ f32x4 sigm4(f32x4 v) { return (f32x4){sigm(v[0]), sigm(v[1]), sigm(v[2]), sigm(v[3])}; }
; #define FOR_ROWS _Pragma("unroll") for (int ai = 0; ai < 2; ++ai) _Pragma("unroll") for (int m = 0; m < 4; ++m)
; __device__ __forceinline__ void epilogue(const int kind, CParams& p, const f32x4 (&acc)[2][2][4][2], const Unit& u, const int wr, const int wc, const int fr_in, const int fq_in) {
;     ...
;     case E_FFN1: {
;         float rsv[2][4];
;         FOR_ROWS { ROWDEF rsv[ai][m] = p.ss2[row]; }
;         FOR_ROWS { ROWDEF
;             const float rs = rsqrtf(rsv[ai][m] * (1.f / 1024.f) + 1e-6f);
;             const f32x4 g0 = acc[ai][0][m][0] * rs, g1 = acc[ai][0][m][1] * rs, u0 = acc[ai][1][m][0] * rs, u1 = acc[ai][1][m][1] * rs;
;             *(u32x4*)(p.hid + row * DFF + u.pn * 128 + cw) = pack8(g0 * sigm4(g0) * u0, g1 * sigm4(g1) * u1);
;         }
;     } break;
	v_pk_mul_f32 v[146:147], v[64:65], v[148:149] op_sel_hi:[1,0]
	v_rcp_f32_e32 v174, v174
	s_nop 0
	v_pk_mul_f32 v[150:151], v[150:151], v[174:175]
	v_pk_mul_f32 v[148:149], v[66:67], v[148:149] op_sel_hi:[1,0]
	v_pk_mul_f32 v[150:151], v[156:157], v[150:151]
	v_rcp_f32_e32 v159, v159
	v_mul_f32_e32 v156, 0xbfb8aa3b, v142
	v_mul_f32_e32 v157, 0xbfb8aa3b, v143
	v_exp_f32_e32 v156, v156
	v_exp_f32_e32 v157, v157
	v_rcp_f32_e32 v158, v158
	v_pk_add_f32 v[156:157], v[156:157], 1.0 op_sel_hi:[1,0]
	v_pk_mul_f32 v[152:153], v[152:153], v[158:159]
	s_nop 0
	v_pk_mul_f32 v[152:153], v[154:155], v[152:153]
	v_mul_f32_e32 v154, 0xbfb8aa3b, v144
	v_mul_f32_e32 v155, 0xbfb8aa3b, v145
	v_rcp_f32_e32 v157, v157
	v_exp_f32_e32 v154, v154
	v_exp_f32_e32 v155, v155
	s_nop 0
	v_pk_add_f32 v[154:155], v[154:155], 1.0 op_sel_hi:[1,0]
	v_rcp_f32_e32 v156, v156
	s_nop 0
	v_pk_mul_f32 v[142:143], v[142:143], v[156:157]
	v_rcp_f32_e32 v155, v155
	v_pk_mul_f32 v[148:149], v[148:149], v[142:143]
	v_cvt_pk_bf16_f32 v142, v152, v153
	v_cvt_pk_bf16_f32 v143, v150, v151
	v_rcp_f32_e32 v154, v154
	s_nop 0
	v_pk_mul_f32 v[144:145], v[144:145], v[154:155]
	s_nop 0
	v_pk_mul_f32 v[144:145], v[146:147], v[144:145]
	v_mad_u64_u32 v[146:147], s[12:13], v140, s14, v[130:131]
	v_mad_i32_i24 v147, v141, s14, v147
	v_lshl_add_u64 v[140:141], v[146:147], 0, s[10:11]
	v_lshl_add_u64 v[140:141], v[140:141], 0, v[132:133]
	v_cvt_pk_bf16_f32 v144, v144, v145
	v_cvt_pk_bf16_f32 v145, v148, v149
	global_store_dwordx4 v[140:141], v[142:145], off
	v_fmamk_f32 v140, v181, 0x3a800000, v193
	v_cmp_gt_f32_e32 vcc, s1, v140
	v_mul_f32_e32 v141, 0x4b800000, v140
	s_nop 0
	v_cndmask_b32_e32 v140, v140, v141, vcc
	v_rsq_f32_e32 v140, v140
	s_nop 0
	v_mul_f32_e32 v141, 0x45800000, v140
	v_cndmask_b32_e32 v146, v140, v141, vcc
	v_pk_mul_f32 v[148:149], v[62:63], v[146:147] op_sel_hi:[1,0]
	v_pk_mul_f32 v[150:151], v[60:61], v[146:147] op_sel_hi:[1,0]
	v_mul_f32_e32 v158, 0xbfb8aa3b, v148
	v_mul_f32_e32 v159, 0xbfb8aa3b, v149
	v_exp_f32_e32 v158, v158
	v_exp_f32_e32 v159, v159
	v_mul_f32_e32 v156, 0xbfb8aa3b, v150
	v_mul_f32_e32 v157, 0xbfb8aa3b, v151
	v_exp_f32_e32 v156, v156
	v_pk_add_f32 v[158:159], v[158:159], 1.0 op_sel_hi:[1,0]
	v_exp_f32_e32 v157, v157
	s_nop 0
	v_pk_add_f32 v[156:157], v[156:157], 1.0 op_sel_hi:[1,0]
	v_pk_mul_f32 v[140:141], v[58:59], v[146:147] op_sel_hi:[1,0]
	v_pk_mul_f32 v[154:155], v[30:31], v[146:147] op_sel_hi:[1,0]
	v_rcp_f32_e32 v159, v159
	v_pk_mul_f32 v[142:143], v[56:57], v[146:147] op_sel_hi:[1,0]
	v_pk_mul_f32 v[152:153], v[28:29], v[146:147] op_sel_hi:[1,0]
	v_pk_mul_f32 v[144:145], v[24:25], v[146:147] op_sel_hi:[1,0]
	v_rcp_f32_e32 v158, v158
	s_nop 0
	v_pk_mul_f32 v[148:149], v[148:149], v[158:159]
	v_pk_mul_f32 v[146:147], v[26:27], v[146:147] op_sel_hi:[1,0]
	v_pk_mul_f32 v[148:149], v[154:155], v[148:149]
	v_rcp_f32_e32 v157, v157
	v_mul_f32_e32 v154, 0xbfb8aa3b, v140
	v_mul_f32_e32 v155, 0xbfb8aa3b, v141
	v_exp_f32_e32 v154, v154
	v_exp_f32_e32 v155, v155
	v_rcp_f32_e32 v156, v156
	v_pk_add_f32 v[154:155], v[154:155], 1.0 op_sel_hi:[1,0]
	v_pk_mul_f32 v[150:151], v[150:151], v[156:157]
	s_nop 0
	v_pk_mul_f32 v[150:151], v[152:153], v[150:151]
	v_mul_f32_e32 v152, 0xbfb8aa3b, v142
	v_mul_f32_e32 v153, 0xbfb8aa3b, v143
	v_rcp_f32_e32 v155, v155
	v_exp_f32_e32 v152, v152
	v_exp_f32_e32 v153, v153
	s_nop 0
	v_pk_add_f32 v[152:153], v[152:153], 1.0 op_sel_hi:[1,0]
	v_rcp_f32_e32 v154, v154
	s_nop 0
	v_pk_mul_f32 v[140:141], v[140:141], v[154:155]
	v_rcp_f32_e32 v153, v153
	v_pk_mul_f32 v[146:147], v[146:147], v[140:141]
	v_cvt_pk_bf16_f32 v140, v150, v151
	v_cvt_pk_bf16_f32 v141, v148, v149
	v_rcp_f32_e32 v152, v152
	s_nop 0
	v_pk_mul_f32 v[142:143], v[142:143], v[152:153]
	s_nop 0
	v_pk_mul_f32 v[142:143], v[144:145], v[142:143]
	v_mad_u64_u32 v[144:145], s[12:13], v138, s14, v[130:131]
	v_mad_i32_i24 v145, v139, s14, v145
	v_lshl_add_u64 v[138:139], v[144:145], 0, s[10:11]
	v_lshl_add_u64 v[138:139], v[138:139], 0, v[132:133]
	v_cvt_pk_bf16_f32 v142, v142, v143
	v_cvt_pk_bf16_f32 v143, v146, v147
	global_store_dwordx4 v[138:139], v[140:143], off
	v_fmamk_f32 v138, v180, 0x3a800000, v193
	v_cmp_gt_f32_e32 vcc, s1, v138
	v_mul_f32_e32 v139, 0x4b800000, v138
	s_nop 0
	v_cndmask_b32_e32 v138, v138, v139, vcc
	v_rsq_f32_e32 v138, v138
	s_nop 0
	v_mul_f32_e32 v139, 0x45800000, v138
	v_cndmask_b32_e32 v144, v138, v139, vcc
	v_pk_mul_f32 v[146:147], v[54:55], v[144:145] op_sel_hi:[1,0]
	v_pk_mul_f32 v[148:149], v[52:53], v[144:145] op_sel_hi:[1,0]
	v_mul_f32_e32 v156, 0xbfb8aa3b, v146
	v_mul_f32_e32 v157, 0xbfb8aa3b, v147
	v_exp_f32_e32 v156, v156
	v_exp_f32_e32 v157, v157
	v_mul_f32_e32 v154, 0xbfb8aa3b, v148
	v_mul_f32_e32 v155, 0xbfb8aa3b, v149
	v_exp_f32_e32 v154, v154
	v_pk_add_f32 v[156:157], v[156:157], 1.0 op_sel_hi:[1,0]
	v_exp_f32_e32 v155, v155
	s_nop 0
	v_pk_add_f32 v[154:155], v[154:155], 1.0 op_sel_hi:[1,0]
	v_pk_mul_f32 v[138:139], v[50:51], v[144:145] op_sel_hi:[1,0]
	v_pk_mul_f32 v[152:153], v[22:23], v[144:145] op_sel_hi:[1,0]
	v_rcp_f32_e32 v157, v157
	v_pk_mul_f32 v[140:141], v[48:49], v[144:145] op_sel_hi:[1,0]
	v_pk_mul_f32 v[150:151], v[20:21], v[144:145] op_sel_hi:[1,0]
	v_pk_mul_f32 v[142:143], v[16:17], v[144:145] op_sel_hi:[1,0]
	v_rcp_f32_e32 v156, v156
	s_nop 0
	v_pk_mul_f32 v[146:147], v[146:147], v[156:157]
	v_pk_mul_f32 v[144:145], v[18:19], v[144:145] op_sel_hi:[1,0]
	v_pk_mul_f32 v[146:147], v[152:153], v[146:147]
	v_rcp_f32_e32 v155, v155
	v_mul_f32_e32 v152, 0xbfb8aa3b, v138
	v_mul_f32_e32 v153, 0xbfb8aa3b, v139
	v_exp_f32_e32 v152, v152
	v_exp_f32_e32 v153, v153
	v_rcp_f32_e32 v154, v154
	v_pk_add_f32 v[152:153], v[152:153], 1.0 op_sel_hi:[1,0]
; __device__ __forceinline__ u32x4 pack8(f32x4 a, f32x4 b) { u32x4 w; w.x = pk2(a[0], a[1]); w.y = pk2(a[2], a[3]); w.z = pk2(b[0], b[1]); w.w = pk2(b[2], b[3]); return w; }
; __device__ __forceinline__ f32x4 sigm4(f32x4 v) { return (f32x4){sigm(v[0]), sigm(v[1]), sigm(v[2]), sigm(v[3])}; }
; #define FOR_ROWS _Pragma("unroll") for (int ai = 0; ai < 2; ++ai) _Pragma("unroll") for (int m = 0; m < 4; ++m)
; __device__ __forceinline__ void epilogue(const int kind, CParams& p, const f32x4 (&acc)[2][2][4][2], const Unit& u, const int wr, const int wc, const int fr_in, const int fq_in) {
;     ...
;     case E_FFN1: {
;         float rsv[2][4];
;         FOR_ROWS { ROWDEF rsv[ai][m] = p.ss2[row]; }
;         FOR_ROWS { ROWDEF
;             const float rs = rsqrtf(rsv[ai][m] * (1.f / 1024.f) + 1e-6f);
;             const f32x4 g0 = acc[ai][0][m][0] * rs, g1 = acc[ai][0][m][1] * rs, u0 = acc[ai][1][m][0] * rs, u1 = acc[ai][1][m][1] * rs;
;             *(u32x4*)(p.hid + row * DFF + u.pn * 128 + cw) = pack8(g0 * sigm4(g0) * u0, g1 * sigm4(g1) * u1);
;         }
;     } break;
	v_pk_mul_f32 v[148:149], v[148:149], v[154:155]
	s_nop 0
	v_pk_mul_f32 v[148:149], v[150:151], v[148:149]
	v_mul_f32_e32 v150, 0xbfb8aa3b, v140
	v_mul_f32_e32 v151, 0xbfb8aa3b, v141
	v_rcp_f32_e32 v153, v153
	v_exp_f32_e32 v150, v150
	v_exp_f32_e32 v151, v151
	s_nop 0
	v_pk_add_f32 v[150:151], v[150:151], 1.0 op_sel_hi:[1,0]
	v_rcp_f32_e32 v152, v152
	s_nop 0
	v_pk_mul_f32 v[138:139], v[138:139], v[152:153]
	v_rcp_f32_e32 v151, v151
	v_pk_mul_f32 v[144:145], v[144:145], v[138:139]
	v_cvt_pk_bf16_f32 v138, v148, v149
	v_cvt_pk_bf16_f32 v139, v146, v147
	v_rcp_f32_e32 v150, v150
	s_nop 0
	v_pk_mul_f32 v[140:141], v[140:141], v[150:151]
	s_nop 0
	v_pk_mul_f32 v[140:141], v[142:143], v[140:141]
	v_mad_u64_u32 v[142:143], s[12:13], v136, s14, v[130:131]
	v_mad_i32_i24 v143, v137, s14, v143
	v_lshl_add_u64 v[136:137], v[142:143], 0, s[10:11]
	v_lshl_add_u64 v[136:137], v[136:137], 0, v[132:133]
	v_cvt_pk_bf16_f32 v140, v140, v141
	v_cvt_pk_bf16_f32 v141, v144, v145
	global_store_dwordx4 v[136:137], v[138:141], off
	v_fmamk_f32 v136, v179, 0x3a800000, v193
	v_cmp_gt_f32_e32 vcc, s1, v136
	v_mul_f32_e32 v137, 0x4b800000, v136
	s_nop 0
	v_cndmask_b32_e32 v136, v136, v137, vcc
	v_rsq_f32_e32 v136, v136
	s_nop 0
	v_mul_f32_e32 v137, 0x45800000, v136
	v_cndmask_b32_e32 v142, v136, v137, vcc
	v_pk_mul_f32 v[144:145], v[46:47], v[142:143] op_sel_hi:[1,0]
	v_pk_mul_f32 v[146:147], v[44:45], v[142:143] op_sel_hi:[1,0]
	v_mul_f32_e32 v154, 0xbfb8aa3b, v144
	v_mul_f32_e32 v155, 0xbfb8aa3b, v145
	v_exp_f32_e32 v154, v154
	v_exp_f32_e32 v155, v155
	v_mul_f32_e32 v152, 0xbfb8aa3b, v146
	v_mul_f32_e32 v153, 0xbfb8aa3b, v147
	v_exp_f32_e32 v152, v152
	v_pk_add_f32 v[154:155], v[154:155], 1.0 op_sel_hi:[1,0]
	v_exp_f32_e32 v153, v153
	s_nop 0
	v_pk_add_f32 v[152:153], v[152:153], 1.0 op_sel_hi:[1,0]
	v_pk_mul_f32 v[136:137], v[42:43], v[142:143] op_sel_hi:[1,0]
	v_pk_mul_f32 v[150:151], v[14:15], v[142:143] op_sel_hi:[1,0]
	v_rcp_f32_e32 v155, v155
	v_pk_mul_f32 v[138:139], v[40:41], v[142:143] op_sel_hi:[1,0]
	v_pk_mul_f32 v[148:149], v[12:13], v[142:143] op_sel_hi:[1,0]
	v_pk_mul_f32 v[140:141], v[8:9], v[142:143] op_sel_hi:[1,0]
	v_rcp_f32_e32 v154, v154
	s_nop 0
	v_pk_mul_f32 v[144:145], v[144:145], v[154:155]
	v_pk_mul_f32 v[142:143], v[10:11], v[142:143] op_sel_hi:[1,0]
	v_pk_mul_f32 v[144:145], v[150:151], v[144:145]
	v_rcp_f32_e32 v153, v153
	v_mul_f32_e32 v150, 0xbfb8aa3b, v136
	v_mul_f32_e32 v151, 0xbfb8aa3b, v137
	v_exp_f32_e32 v150, v150
	v_exp_f32_e32 v151, v151
	v_rcp_f32_e32 v152, v152
	v_pk_add_f32 v[150:151], v[150:151], 1.0 op_sel_hi:[1,0]
	v_pk_mul_f32 v[146:147], v[146:147], v[152:153]
	s_nop 0
	v_pk_mul_f32 v[146:147], v[148:149], v[146:147]
	v_mul_f32_e32 v148, 0xbfb8aa3b, v138
	v_mul_f32_e32 v149, 0xbfb8aa3b, v139
	v_rcp_f32_e32 v151, v151
	v_exp_f32_e32 v148, v148
	v_exp_f32_e32 v149, v149
	s_nop 0
	v_pk_add_f32 v[148:149], v[148:149], 1.0 op_sel_hi:[1,0]
	v_rcp_f32_e32 v150, v150
	s_nop 0
	v_pk_mul_f32 v[136:137], v[136:137], v[150:151]
	v_rcp_f32_e32 v149, v149
	v_pk_mul_f32 v[142:143], v[142:143], v[136:137]
	v_cvt_pk_bf16_f32 v136, v146, v147
	v_cvt_pk_bf16_f32 v137, v144, v145
	v_rcp_f32_e32 v148, v148
	s_nop 0
	v_pk_mul_f32 v[138:139], v[138:139], v[148:149]
	s_nop 0
	v_pk_mul_f32 v[138:139], v[140:141], v[138:139]
	v_mad_u64_u32 v[140:141], s[12:13], v134, s14, v[130:131]
	v_mad_i32_i24 v141, v135, s14, v141
	v_lshl_add_u64 v[134:135], v[140:141], 0, s[10:11]
	v_lshl_add_u64 v[134:135], v[134:135], 0, v[132:133]
	v_cvt_pk_bf16_f32 v138, v138, v139
	v_cvt_pk_bf16_f32 v139, v142, v143
	global_store_dwordx4 v[134:135], v[136:139], off
	v_fmamk_f32 v134, v178, 0x3a800000, v193
	v_cmp_gt_f32_e32 vcc, s1, v134
	v_mul_f32_e32 v135, 0x4b800000, v134
	v_mad_u64_u32 v[130:131], s[12:13], v128, s14, v[130:131]
	v_cndmask_b32_e32 v134, v134, v135, vcc
	v_rsq_f32_e32 v134, v134
	v_mad_i32_i24 v131, v129, s14, v131
	v_lshl_add_u64 v[128:129], v[130:131], 0, s[10:11]
	v_lshl_add_u64 v[128:129], v[128:129], 0, v[132:133]
	v_mul_f32_e32 v135, 0x45800000, v134
	v_cndmask_b32_e32 v140, v134, v135, vcc
	v_pk_mul_f32 v[142:143], v[38:39], v[140:141] op_sel_hi:[1,0]
	v_pk_mul_f32 v[144:145], v[36:37], v[140:141] op_sel_hi:[1,0]
	v_mul_f32_e32 v152, 0xbfb8aa3b, v142
	v_mul_f32_e32 v153, 0xbfb8aa3b, v143
	v_exp_f32_e32 v152, v152
	v_exp_f32_e32 v153, v153
	v_mul_f32_e32 v150, 0xbfb8aa3b, v144
	v_mul_f32_e32 v151, 0xbfb8aa3b, v145
	v_exp_f32_e32 v150, v150
	v_pk_add_f32 v[152:153], v[152:153], 1.0 op_sel_hi:[1,0]
	v_exp_f32_e32 v151, v151
	s_nop 0
	v_pk_add_f32 v[150:151], v[150:151], 1.0 op_sel_hi:[1,0]
	v_pk_mul_f32 v[134:135], v[34:35], v[140:141] op_sel_hi:[1,0]
	v_pk_mul_f32 v[148:149], v[6:7], v[140:141] op_sel_hi:[1,0]
	v_rcp_f32_e32 v153, v153
	v_pk_mul_f32 v[136:137], v[32:33], v[140:141] op_sel_hi:[1,0]
	v_pk_mul_f32 v[146:147], v[4:5], v[140:141] op_sel_hi:[1,0]
	v_pk_mul_f32 v[138:139], v[0:1], v[140:141] op_sel_hi:[1,0]
	v_rcp_f32_e32 v152, v152
	s_nop 0
	v_pk_mul_f32 v[142:143], v[142:143], v[152:153]
	v_pk_mul_f32 v[140:141], v[2:3], v[140:141] op_sel_hi:[1,0]
	v_pk_mul_f32 v[142:143], v[148:149], v[142:143]
	v_rcp_f32_e32 v151, v151
	v_mul_f32_e32 v148, 0xbfb8aa3b, v134
	v_mul_f32_e32 v149, 0xbfb8aa3b, v135
	v_exp_f32_e32 v148, v148
	v_exp_f32_e32 v149, v149
	v_rcp_f32_e32 v150, v150
	v_pk_add_f32 v[148:149], v[148:149], 1.0 op_sel_hi:[1,0]
	v_pk_mul_f32 v[144:145], v[144:145], v[150:151]
	s_nop 0
	v_pk_mul_f32 v[144:145], v[146:147], v[144:145]
	v_mul_f32_e32 v146, 0xbfb8aa3b, v136
	v_mul_f32_e32 v147, 0xbfb8aa3b, v137
	v_rcp_f32_e32 v149, v149
	v_exp_f32_e32 v146, v146
	v_exp_f32_e32 v147, v147
	s_mov_b64 s[10:11], 0
	v_pk_add_f32 v[146:147], v[146:147], 1.0 op_sel_hi:[1,0]
	v_rcp_f32_e32 v148, v148
	s_nop 0
	v_pk_mul_f32 v[134:135], v[134:135], v[148:149]
	v_rcp_f32_e32 v147, v147
	v_pk_mul_f32 v[140:141], v[140:141], v[134:135]
	v_cvt_pk_bf16_f32 v134, v144, v145
	v_cvt_pk_bf16_f32 v135, v142, v143
	v_rcp_f32_e32 v146, v146
	s_nop 0
	v_pk_mul_f32 v[136:137], v[136:137], v[146:147]
	s_nop 0
	v_pk_mul_f32 v[136:137], v[138:139], v[136:137]
	s_nop 0
	v_cvt_pk_bf16_f32 v136, v136, v137
	v_cvt_pk_bf16_f32 v137, v140, v141
	global_store_dwordx4 v[128:129], v[134:137], off
	s_branch .LBB0_645
